# P1/P7: 6 of 8 epilogue stores trickled one per K-loop iteration, issue segment staggered by rank; countdown-relaxed waits
# baseline (speedup 1.0000x reference)
; #define PG8_STAGE(bufoff, gbase, voff) do { _Pragma("unroll") for (int _i = 0; _i < 2; ++_i) \
;         __builtin_amdgcn_global_load_lds((const unsigned*)((const char*)(gbase) + (voff)[_i]), (LAS unsigned*)(lds + (bufoff) + ldsw + _i * 8192), 16, 0, 0); } while (0)
; #define PG8_WAIT_V(n) asm volatile("s_waitcnt vmcnt(" #n ")" ::: "memory")
; #define PG8_BAR __builtin_amdgcn_s_barrier()
; template <class Epi, class Sched, bool ALIGN_EPI>
; __device__ __forceinline__ void gemm_phase(LAS unsigned char* lds, const Gemm g, const Sched& S, const Epi& E) {
;     ...
;     const char* cA = (const char*)g.A + (size_t)cur.pm * tstepA; const char* cB = (const char*)g.Bt + (size_t)cur.pn * tstepB;
;     PG8_STAGE(PG8_SB(0, 0), cB, voffB); PG8_STAGE(PG8_SB(0, 1), cB + hstepB, voffB); PG8_STAGE(PG8_SA(0, 0), cA, voffA); PG8_STAGE(PG8_SA(0, 1), cA + hstepA, voffA);
;     if (wr == 1) PG8_BAR;
;     PG8_WAIT_V(2); PG8_BAR;
;     PG8_STAGE(PG8_SB(1, 0), cB + kstep, voffB); PG8_STAGE(PG8_SA(1, 0), cA + kstep, voffA); PG8_STAGE(PG8_SB(1, 1), cB + hstepB + kstep, voffB);
;     PG8_WAIT_V(6); PG8_BAR;
.LBB0_601:
	s_lshl_b32 s8, s8, 5
	s_and_b32 s14, s8, 0x60
	s_mov_b64 s[8:9], 0x80
	s_add_i32 m0, s21, 0x18000
	v_lshl_add_u64 v[6:7], v[6:7], 0, s[8:9]
	s_lshl_b32 s11, s10, 13
	s_lshl_b32 s15, s14, 7
	global_load_lds_dwordx4 v[6:7], off
	v_lshl_add_u64 v[4:5], v[4:5], 0, s[8:9]
	s_add_i32 m0, s21, 0x1a000
	s_add_i32 s38, s21, 0x8000
	s_add_i32 s39, s21, 0xa000
	global_load_lds_dwordx4 v[4:5], off
	v_lshl_add_u64 v[0:1], v[0:1], 0, s[8:9]
	s_mov_b32 m0, s38
	s_add_u32 s12, s24, 0x40080
	global_load_lds_dwordx4 v[0:1], off
	v_lshl_add_u64 v[0:1], v[2:3], 0, s[8:9]
	s_mov_b32 m0, s39
	s_addc_u32 s13, s25, 0
	global_load_lds_dwordx4 v[0:1], off
	s_add_i32 m0, s21, 0x1c000
	v_lshl_add_u64 v[0:1], s[12:13], 0, v[132:133]
	global_load_lds_dwordx4 v[0:1], off
	v_lshl_add_u64 v[0:1], s[12:13], 0, v[128:129]
	s_add_i32 m0, s21, 0x1e000
	s_sext_i32_i8 s47, s2
	global_load_lds_dwordx4 v[0:1], off
	s_waitcnt vmcnt(8)
	s_barrier
	v_and_b32_e32 v0, 15, v153
	v_lshlrev_b32_e32 v1, 1, v11
	v_lshl_or_b32 v144, s10, 6, v0
	v_lshl_or_b32 v2, v0, 6, v1
	v_lshlrev_b32_e32 v0, 2, v0
	v_and_b32_e32 v3, 32, v0
	v_bitop3_b32 v2, v2, s11, v3 bitop3:0xde
	v_lshlrev_b32_e32 v3, 6, v153
	s_movk_i32 s2, 0x3c0
	v_and_or_b32 v1, v3, s2, v1
	s_lshl_b32 s2, s10, 8
	s_add_i32 s2, s2, 0
	v_lshlrev_b32_e32 v3, 2, v153
	s_add_i32 s2, s2, 0x20000
	v_and_b32_e32 v3, 32, v3
	v_add_u32_e32 v146, s2, v0
	v_lshlrev_b32_e32 v0, 8, v153
	v_bitop3_b32 v145, s15, v1, v3 bitop3:0xf6
	v_and_b32_e32 v0, 0x38000, v0
	v_lshlrev_b32_e32 v1, 11, v12
	v_or3_b32 v0, v9, v0, v1
	v_add_u32_e32 v136, v0, v10
	v_lshlrev_b32_e32 v0, 4, v8
	s_waitcnt vmcnt(6)
	s_cmpk_lt_u32 s3, 0x100
	v_and_b32_e32 v0, 0x78000, v0
	s_cselect_b64 s[10:11], -1, 0
	v_or3_b32 v0, v9, v0, v1
	s_add_i32 s40, 0, 0x10000
	s_add_i32 s41, 0, 0x14000
	v_or_b32_e32 v147, s14, v11
	v_mov_b32_e32 v137, v133
	v_add_u32_e32 v138, v0, v10
	v_mov_b32_e32 v139, v133
	v_mov_b64_e32 v[140:141], 0xb00
	v_mov_b64_e32 v[142:143], 0xaff
	v_add_u32_e32 v148, s40, v145
	v_add_u32_e32 v149, s41, v145
	v_add_u32_e32 v150, 0, v2
	s_movk_i32 s42, 0x1600
	s_mov_b32 s43, 0
	s_barrier
	s_mov_b32 s70, 0
	s_mov_b32 s71, 0
	v_readlane_b32 s79, v245, 0
	s_nop 1
	s_and_b32 s79, s79, 3
	s_branch .LBB0_604

.Lpk607_r1:
	s_waitcnt vmcnt(10)

; __device__ __forceinline__ unsigned cvt_pk_bf16(float lo, float hi) { unsigned r; asm volatile("v_cvt_pk_bf16_f32 %0, %1, %2" : "=v"(r) : "v"(lo), "v"(hi)); return r; }
;     __device__ __forceinline__ void operator()(Acc& acc, const Unit& u, int wr, int wc, int fr, int fq) const {
;     ...
;                 u32x4 w; w.x = cvt_pk_bf16(o[0][0], o[0][1]); w.y = cvt_pk_bf16(o[0][2], o[0][3]); w.z = cvt_pk_bf16(o[1][0], o[1][1]); w.w = cvt_pk_bf16(o[1][2], o[1][3]);
;                 *(u32x4*)(O + (size_t)row * DFF + col0) = w;
.Lpk607_j2:
	s_mov_b32 s101, 0
	s_mov_b32 s71, 0
	s_waitcnt lgkmcnt(0)
	s_setprio 1
	s_barrier
	v_mfma_f32_16x16x32_bf16 v[60:63], v[154:157], v[186:189], 0
	v_mfma_f32_16x16x32_bf16 v[52:55], v[162:165], v[186:189], 0
	v_mfma_f32_16x16x32_bf16 v[44:47], v[154:157], v[194:197], 0
	v_mfma_f32_16x16x32_bf16 v[36:39], v[162:165], v[194:197], 0
	v_mfma_f32_16x16x32_bf16 v[28:31], v[154:157], v[202:205], 0
	v_mfma_f32_16x16x32_bf16 v[20:23], v[162:165], v[202:205], 0
	v_mfma_f32_16x16x32_bf16 v[12:15], v[154:157], v[210:213], 0
	v_mfma_f32_16x16x32_bf16 v[4:7], v[162:165], v[210:213], 0
	v_mfma_f32_16x16x32_bf16 v[60:63], v[158:161], v[190:193], v[60:63]
	v_mfma_f32_16x16x32_bf16 v[52:55], v[166:169], v[190:193], v[52:55]
	v_mfma_f32_16x16x32_bf16 v[44:47], v[158:161], v[198:201], v[44:47]
	v_mfma_f32_16x16x32_bf16 v[36:39], v[166:169], v[198:201], v[36:39]
	v_mfma_f32_16x16x32_bf16 v[28:31], v[158:161], v[206:209], v[28:31]
	v_mfma_f32_16x16x32_bf16 v[20:23], v[166:169], v[206:209], v[20:23]
	v_mfma_f32_16x16x32_bf16 v[12:15], v[158:161], v[214:217], v[12:15]
	v_mfma_f32_16x16x32_bf16 v[4:7], v[166:169], v[214:217], v[4:7]
	s_setprio 0
	s_setprio 1
	v_mfma_f32_16x16x32_bf16 v[56:59], v[170:173], v[186:189], 0
	v_mfma_f32_16x16x32_bf16 v[48:51], v[178:181], v[186:189], 0
	v_mfma_f32_16x16x32_bf16 v[40:43], v[170:173], v[194:197], 0
	v_mfma_f32_16x16x32_bf16 v[32:35], v[178:181], v[194:197], 0
	v_mfma_f32_16x16x32_bf16 v[24:27], v[170:173], v[202:205], 0
	v_mfma_f32_16x16x32_bf16 v[16:19], v[178:181], v[202:205], 0
	v_mfma_f32_16x16x32_bf16 v[8:11], v[170:173], v[210:213], 0
	v_mfma_f32_16x16x32_bf16 v[0:3], v[178:181], v[210:213], 0
	v_mfma_f32_16x16x32_bf16 v[56:59], v[174:177], v[190:193], v[56:59]
	v_mfma_f32_16x16x32_bf16 v[48:51], v[182:185], v[190:193], v[48:51]
	v_mfma_f32_16x16x32_bf16 v[40:43], v[174:177], v[198:201], v[40:43]
	v_mfma_f32_16x16x32_bf16 v[32:35], v[182:185], v[198:201], v[32:35]
	v_mfma_f32_16x16x32_bf16 v[24:27], v[174:177], v[206:209], v[24:27]
	v_mfma_f32_16x16x32_bf16 v[16:19], v[182:185], v[206:209], v[16:19]
	v_mfma_f32_16x16x32_bf16 v[8:11], v[174:177], v[214:217], v[8:11]
	v_mfma_f32_16x16x32_bf16 v[0:3], v[182:185], v[214:217], v[0:3]
	s_barrier
	s_setprio 0
	s_branch .Lpk607_seg3
.LBB0_607:
	ds_read_b128 v[154:157], v148
	ds_read_b128 v[158:161], v148 offset:1024
	ds_read_b128 v[162:165], v148 offset:2048
	ds_read_b128 v[166:169], v148 offset:3072
	ds_read_b128 v[170:173], v149
	ds_read_b128 v[174:177], v149 offset:1024
	ds_read_b128 v[178:181], v149 offset:2048
	ds_read_b128 v[182:185], v149 offset:3072
	s_add_u32 s24, s22, 0xfffc0080
	s_addc_u32 s25, s23, -1
	s_cmp_eq_u32 s52, 12
	s_cselect_b32 s27, s15, s25
	s_cselect_b32 s26, s48, s24
	s_cselect_b32 s25, s13, s51
	s_cselect_b32 s24, s49, s50
	v_lshl_add_u64 v[218:219], s[22:23], 0, v[136:137]
	s_add_i32 m0, s21, 0xc000
	ds_read_b128 v[186:189], v150
	ds_read_b128 v[190:193], v150 offset:1024
	ds_read_b128 v[194:197], v150 offset:2048
	ds_read_b128 v[198:201], v150 offset:3072
	ds_read_b128 v[202:205], v150 offset:4096
	ds_read_b128 v[206:209], v150 offset:5120
	ds_read_b128 v[210:213], v150 offset:6144
	ds_read_b128 v[214:217], v150 offset:7168
	global_load_lds_dwordx4 v[218:219], off
	v_lshl_add_u64 v[218:219], s[22:23], 0, v[138:139]
	s_add_i32 m0, s21, 0xe000
	s_nop 0
	global_load_lds_dwordx4 v[218:219], off
	s_cmp_lg_u32 s79, 0
	s_cbranch_scc1 .Ltr607_0_w
	s_cmp_eq_u32 s70, 0
	s_cbranch_scc1 .Ltr607_0_w
	s_cmp_eq_u32 s70, 1
	s_cbranch_scc1 .Ltr607_0_s1
	s_cmp_eq_u32 s70, 2
	s_cbranch_scc1 .Ltr607_0_s2
	s_cmp_eq_u32 s70, 3
	s_cbranch_scc1 .Ltr607_0_s3
	s_cmp_eq_u32 s70, 4
	s_cbranch_scc1 .Ltr607_0_s4
	s_cmp_eq_u32 s70, 5
	s_cbranch_scc1 .Ltr607_0_s5
	v_add_u32_e32 v255, 0xf2000, v254
	global_store_dwordx4 v255, v[250:253], s[64:65]
	s_branch .Ltr607_0_d
.Ltr607_0_s1:
	v_add_u32_e32 v255, 0x2c000, v254
	global_store_dwordx4 v255, v[228:231], s[64:65]
	s_branch .Ltr607_0_d
.Ltr607_0_s2:
	v_add_u32_e32 v255, 0x42000, v254
	global_store_dwordx4 v255, v[232:235], s[64:65]
	s_branch .Ltr607_0_d
.Ltr607_0_s3:
	v_add_u32_e32 v255, 0xb0000, v254
	global_store_dwordx4 v255, v[236:239], s[64:65]
	s_branch .Ltr607_0_d
.Ltr607_0_s4:
	v_add_u32_e32 v255, 0xc6000, v254
	global_store_dwordx4 v255, v[240:243], s[64:65]
	s_branch .Ltr607_0_d
.Ltr607_0_s5:
	v_add_u32_e32 v255, 0xdc000, v254
	global_store_dwordx4 v255, v[246:249], s[64:65]
.Ltr607_0_d:
	s_add_i32 s70, s70, 1
	s_cmp_gt_u32 s70, 6
	s_cselect_b32 s70, 0, s70
	s_mov_b32 s71, 3
.Ltr607_0_w:
	s_cmp_eq_u32 s71, 0
	s_cbranch_scc1 .Ltr607_0_p
	s_sub_u32 s71, s71, 1
	s_waitcnt vmcnt(9)
	s_branch .Ltr607_0_j
.Ltr607_0_p:
	s_waitcnt vmcnt(8)
.Ltr607_0_j:
	s_waitcnt lgkmcnt(0)
	s_setprio 1
	s_barrier
	v_mfma_f32_16x16x32_bf16 v[124:127], v[154:157], v[186:189], v[124:127]
	v_mfma_f32_16x16x32_bf16 v[116:119], v[162:165], v[186:189], v[116:119]
	v_mfma_f32_16x16x32_bf16 v[108:111], v[154:157], v[194:197], v[108:111]
	v_mfma_f32_16x16x32_bf16 v[100:103], v[162:165], v[194:197], v[100:103]
	v_mfma_f32_16x16x32_bf16 v[92:95], v[154:157], v[202:205], v[92:95]
	v_mfma_f32_16x16x32_bf16 v[84:87], v[162:165], v[202:205], v[84:87]
	v_mfma_f32_16x16x32_bf16 v[76:79], v[154:157], v[210:213], v[76:79]
	v_mfma_f32_16x16x32_bf16 v[68:71], v[162:165], v[210:213], v[68:71]
	v_mfma_f32_16x16x32_bf16 v[124:127], v[158:161], v[190:193], v[124:127]
	v_mfma_f32_16x16x32_bf16 v[116:119], v[166:169], v[190:193], v[116:119]
	v_mfma_f32_16x16x32_bf16 v[108:111], v[158:161], v[198:201], v[108:111]
	v_mfma_f32_16x16x32_bf16 v[100:103], v[166:169], v[198:201], v[100:103]
	v_mfma_f32_16x16x32_bf16 v[92:95], v[158:161], v[206:209], v[92:95]
	v_mfma_f32_16x16x32_bf16 v[84:87], v[166:169], v[206:209], v[84:87]
	v_mfma_f32_16x16x32_bf16 v[76:79], v[158:161], v[214:217], v[76:79]
	v_mfma_f32_16x16x32_bf16 v[68:71], v[166:169], v[214:217], v[68:71]
	s_setprio 0
	s_setprio 1
	v_mfma_f32_16x16x32_bf16 v[120:123], v[170:173], v[186:189], v[120:123]
	v_mfma_f32_16x16x32_bf16 v[112:115], v[178:181], v[186:189], v[112:115]
	v_mfma_f32_16x16x32_bf16 v[104:107], v[170:173], v[194:197], v[104:107]
	v_mfma_f32_16x16x32_bf16 v[96:99], v[178:181], v[194:197], v[96:99]
	v_mfma_f32_16x16x32_bf16 v[88:91], v[170:173], v[202:205], v[88:91]
	v_mfma_f32_16x16x32_bf16 v[80:83], v[178:181], v[202:205], v[80:83]
	v_mfma_f32_16x16x32_bf16 v[72:75], v[170:173], v[210:213], v[72:75]
	v_mfma_f32_16x16x32_bf16 v[64:67], v[178:181], v[210:213], v[64:67]
	v_mfma_f32_16x16x32_bf16 v[120:123], v[174:177], v[190:193], v[120:123]
	v_mfma_f32_16x16x32_bf16 v[112:115], v[182:185], v[190:193], v[112:115]
	v_mfma_f32_16x16x32_bf16 v[104:107], v[174:177], v[198:201], v[104:107]
	v_mfma_f32_16x16x32_bf16 v[96:99], v[182:185], v[198:201], v[96:99]
	v_mfma_f32_16x16x32_bf16 v[88:91], v[174:177], v[206:209], v[88:91]
	v_mfma_f32_16x16x32_bf16 v[80:83], v[182:185], v[206:209], v[80:83]
	v_mfma_f32_16x16x32_bf16 v[72:75], v[174:177], v[214:217], v[72:75]
	v_mfma_f32_16x16x32_bf16 v[64:67], v[182:185], v[214:217], v[64:67]
	s_barrier
	s_setprio 0
	s_add_i32 s53, s40, s28
	v_lshl_add_u64 v[218:219], s[24:25], 0, v[132:133]
	s_mov_b32 m0, s53
	ds_read_b128 v[186:189], v150 offset:16384
	ds_read_b128 v[190:193], v150 offset:17408
	global_load_lds_dwordx4 v[218:219], off
	s_add_i32 m0, s53, 0x2000
	s_add_u32 s66, s24, 0x40000
	v_lshl_add_u64 v[220:221], s[24:25], 0, v[128:129]
	s_addc_u32 s67, s25, 0
	s_add_i32 s53, s41, s28
	ds_read_b128 v[194:197], v150 offset:18432
	ds_read_b128 v[198:201], v150 offset:19456
	global_load_lds_dwordx4 v[220:221], off
	v_lshl_add_u64 v[222:223], s[66:67], 0, v[132:133]
	s_mov_b32 m0, s53
	v_lshl_add_u64 v[224:225], s[26:27], 0, v[130:131]
	ds_read_b128 v[202:205], v150 offset:20480
	global_load_lds_dwordx4 v[222:223], off
	v_lshl_add_u64 v[222:223], s[66:67], 0, v[128:129]
	s_add_i32 m0, s53, 0x2000
	ds_read_b128 v[206:209], v150 offset:21504
	global_load_lds_dwordx4 v[222:223], off
	v_lshl_add_u64 v[222:223], s[26:27], 0, v[134:135]
	s_mov_b32 m0, s21
	ds_read_b128 v[210:213], v150 offset:22528
	global_load_lds_dwordx4 v[222:223], off
	s_mov_b32 m0, s35
	ds_read_b128 v[214:217], v150 offset:23552
	global_load_lds_dwordx4 v[224:225], off
	s_cmp_lg_u32 s79, 1
	s_cbranch_scc1 .Ltr607_1_w
	s_cmp_eq_u32 s70, 0
	s_cbranch_scc1 .Ltr607_1_w
	s_cmp_eq_u32 s70, 1
	s_cbranch_scc1 .Ltr607_1_s1
	s_cmp_eq_u32 s70, 2
	s_cbranch_scc1 .Ltr607_1_s2
	s_cmp_eq_u32 s70, 3
	s_cbranch_scc1 .Ltr607_1_s3
	s_cmp_eq_u32 s70, 4
	s_cbranch_scc1 .Ltr607_1_s4
	s_cmp_eq_u32 s70, 5
	s_cbranch_scc1 .Ltr607_1_s5
	v_add_u32_e32 v255, 0xf2000, v254
	global_store_dwordx4 v255, v[250:253], s[64:65]
	s_branch .Ltr607_1_d

.Ltr607_1_j:
	s_waitcnt lgkmcnt(0)
	s_setprio 1
	s_barrier
	v_mfma_f32_16x16x32_bf16 v[60:63], v[154:157], v[186:189], v[60:63]
	v_mfma_f32_16x16x32_bf16 v[52:55], v[162:165], v[186:189], v[52:55]
	v_mfma_f32_16x16x32_bf16 v[44:47], v[154:157], v[194:197], v[44:47]
	v_mfma_f32_16x16x32_bf16 v[36:39], v[162:165], v[194:197], v[36:39]
	v_mfma_f32_16x16x32_bf16 v[28:31], v[154:157], v[202:205], v[28:31]
	v_mfma_f32_16x16x32_bf16 v[20:23], v[162:165], v[202:205], v[20:23]
	v_mfma_f32_16x16x32_bf16 v[12:15], v[154:157], v[210:213], v[12:15]
	v_mfma_f32_16x16x32_bf16 v[4:7], v[162:165], v[210:213], v[4:7]
	v_mfma_f32_16x16x32_bf16 v[60:63], v[158:161], v[190:193], v[60:63]
	v_mfma_f32_16x16x32_bf16 v[52:55], v[166:169], v[190:193], v[52:55]
	v_mfma_f32_16x16x32_bf16 v[44:47], v[158:161], v[198:201], v[44:47]
	v_mfma_f32_16x16x32_bf16 v[36:39], v[166:169], v[198:201], v[36:39]
	v_mfma_f32_16x16x32_bf16 v[28:31], v[158:161], v[206:209], v[28:31]
	v_mfma_f32_16x16x32_bf16 v[20:23], v[166:169], v[206:209], v[20:23]
	v_mfma_f32_16x16x32_bf16 v[12:15], v[158:161], v[214:217], v[12:15]
	v_mfma_f32_16x16x32_bf16 v[4:7], v[166:169], v[214:217], v[4:7]
	s_setprio 0
	s_setprio 1
	v_mfma_f32_16x16x32_bf16 v[56:59], v[170:173], v[186:189], v[56:59]
	v_mfma_f32_16x16x32_bf16 v[48:51], v[178:181], v[186:189], v[48:51]
	v_mfma_f32_16x16x32_bf16 v[40:43], v[170:173], v[194:197], v[40:43]
	v_mfma_f32_16x16x32_bf16 v[32:35], v[178:181], v[194:197], v[32:35]
	v_mfma_f32_16x16x32_bf16 v[24:27], v[170:173], v[202:205], v[24:27]
	v_mfma_f32_16x16x32_bf16 v[16:19], v[178:181], v[202:205], v[16:19]
	v_mfma_f32_16x16x32_bf16 v[8:11], v[170:173], v[210:213], v[8:11]
	v_mfma_f32_16x16x32_bf16 v[0:3], v[178:181], v[210:213], v[0:3]
	v_mfma_f32_16x16x32_bf16 v[56:59], v[174:177], v[190:193], v[56:59]
	v_mfma_f32_16x16x32_bf16 v[48:51], v[182:185], v[190:193], v[48:51]
	v_mfma_f32_16x16x32_bf16 v[40:43], v[174:177], v[198:201], v[40:43]
	v_mfma_f32_16x16x32_bf16 v[32:35], v[182:185], v[198:201], v[32:35]
	v_mfma_f32_16x16x32_bf16 v[24:27], v[174:177], v[206:209], v[24:27]
	v_mfma_f32_16x16x32_bf16 v[16:19], v[182:185], v[206:209], v[16:19]
	v_mfma_f32_16x16x32_bf16 v[8:11], v[174:177], v[214:217], v[8:11]
	v_mfma_f32_16x16x32_bf16 v[0:3], v[182:185], v[214:217], v[0:3]
	s_barrier
	s_setprio 0
.Lpk607_seg3:
	s_add_i32 s53, 0, 0x18000
	v_add_u32_e32 v151, s53, v145
	s_add_i32 s54, 0, 0x1c000
	ds_read_b128 v[154:157], v151
	ds_read_b128 v[158:161], v151 offset:1024
	ds_read_b128 v[162:165], v151 offset:2048
	ds_read_b128 v[166:169], v151 offset:3072
	v_add_u32_e32 v151, s54, v145
	ds_read_b128 v[170:173], v151
	ds_read_b128 v[174:177], v151 offset:1024
	ds_read_b128 v[178:181], v151 offset:2048
	ds_read_b128 v[182:185], v151 offset:3072
	s_add_u32 s26, s26, 0x40000
	s_addc_u32 s27, s27, 0
	s_mov_b32 m0, s36
	v_lshl_add_u64 v[226:227], s[26:27], 0, v[134:135]
	ds_read_b128 v[186:189], v150 offset:32768
	ds_read_b128 v[190:193], v150 offset:33792
	ds_read_b128 v[194:197], v150 offset:34816
	ds_read_b128 v[198:201], v150 offset:35840
	ds_read_b128 v[202:205], v150 offset:36864
	ds_read_b128 v[206:209], v150 offset:37888
	ds_read_b128 v[210:213], v150 offset:38912
	ds_read_b128 v[214:217], v150 offset:39936
	global_load_lds_dwordx4 v[226:227], off
	v_lshl_add_u64 v[226:227], s[26:27], 0, v[130:131]
	s_mov_b32 m0, s37
	s_nop 0
	global_load_lds_dwordx4 v[226:227], off
	s_cmp_lg_u32 s79, 2
	s_cbranch_scc1 .Ltr607_2_w
	s_cmp_eq_u32 s70, 0
	s_cbranch_scc1 .Ltr607_2_w
	s_cmp_eq_u32 s70, 1
	s_cbranch_scc1 .Ltr607_2_s1
	s_cmp_eq_u32 s70, 2
	s_cbranch_scc1 .Ltr607_2_s2
	s_cmp_eq_u32 s70, 3
	s_cbranch_scc1 .Ltr607_2_s3
	s_cmp_eq_u32 s70, 4
	s_cbranch_scc1 .Ltr607_2_s4
	s_cmp_eq_u32 s70, 5
	s_cbranch_scc1 .Ltr607_2_s5
	v_add_u32_e32 v255, 0xf2000, v254
	global_store_dwordx4 v255, v[250:253], s[64:65]
	s_branch .Ltr607_2_d

.Ltr607_2_j:
	s_waitcnt lgkmcnt(0)
	s_setprio 1
	s_barrier
	v_mfma_f32_16x16x32_bf16 v[124:127], v[154:157], v[186:189], v[124:127]
	v_mfma_f32_16x16x32_bf16 v[116:119], v[162:165], v[186:189], v[116:119]
	v_mfma_f32_16x16x32_bf16 v[108:111], v[154:157], v[194:197], v[108:111]
	v_mfma_f32_16x16x32_bf16 v[100:103], v[162:165], v[194:197], v[100:103]
	v_mfma_f32_16x16x32_bf16 v[92:95], v[154:157], v[202:205], v[92:95]
	v_mfma_f32_16x16x32_bf16 v[84:87], v[162:165], v[202:205], v[84:87]
	v_mfma_f32_16x16x32_bf16 v[76:79], v[154:157], v[210:213], v[76:79]
	v_mfma_f32_16x16x32_bf16 v[68:71], v[162:165], v[210:213], v[68:71]
	v_mfma_f32_16x16x32_bf16 v[124:127], v[158:161], v[190:193], v[124:127]
	v_mfma_f32_16x16x32_bf16 v[116:119], v[166:169], v[190:193], v[116:119]
	v_mfma_f32_16x16x32_bf16 v[108:111], v[158:161], v[198:201], v[108:111]
	v_mfma_f32_16x16x32_bf16 v[100:103], v[166:169], v[198:201], v[100:103]
	v_mfma_f32_16x16x32_bf16 v[92:95], v[158:161], v[206:209], v[92:95]
	v_mfma_f32_16x16x32_bf16 v[84:87], v[166:169], v[206:209], v[84:87]
	v_mfma_f32_16x16x32_bf16 v[76:79], v[158:161], v[214:217], v[76:79]
	v_mfma_f32_16x16x32_bf16 v[68:71], v[166:169], v[214:217], v[68:71]
	s_setprio 0
	s_setprio 1
	v_mfma_f32_16x16x32_bf16 v[120:123], v[170:173], v[186:189], v[120:123]
	v_mfma_f32_16x16x32_bf16 v[112:115], v[178:181], v[186:189], v[112:115]
	v_mfma_f32_16x16x32_bf16 v[104:107], v[170:173], v[194:197], v[104:107]
	v_mfma_f32_16x16x32_bf16 v[96:99], v[178:181], v[194:197], v[96:99]
	v_mfma_f32_16x16x32_bf16 v[88:91], v[170:173], v[202:205], v[88:91]
	v_mfma_f32_16x16x32_bf16 v[80:83], v[178:181], v[202:205], v[80:83]
	v_mfma_f32_16x16x32_bf16 v[72:75], v[170:173], v[210:213], v[72:75]
	v_mfma_f32_16x16x32_bf16 v[64:67], v[178:181], v[210:213], v[64:67]
	v_mfma_f32_16x16x32_bf16 v[120:123], v[174:177], v[190:193], v[120:123]
	v_mfma_f32_16x16x32_bf16 v[112:115], v[182:185], v[190:193], v[112:115]
	v_mfma_f32_16x16x32_bf16 v[104:107], v[174:177], v[198:201], v[104:107]
	v_mfma_f32_16x16x32_bf16 v[96:99], v[182:185], v[198:201], v[96:99]
	v_mfma_f32_16x16x32_bf16 v[88:91], v[174:177], v[206:209], v[88:91]
	v_mfma_f32_16x16x32_bf16 v[80:83], v[182:185], v[206:209], v[80:83]
	v_mfma_f32_16x16x32_bf16 v[72:75], v[174:177], v[214:217], v[72:75]
	v_mfma_f32_16x16x32_bf16 v[64:67], v[182:185], v[214:217], v[64:67]
	s_barrier
	s_setprio 0
	s_add_i32 s26, s53, s28
	v_lshl_add_u64 v[218:219], v[218:219], 0, s[8:9]
	s_mov_b32 m0, s26
	ds_read_b128 v[186:189], v150 offset:49152
	ds_read_b128 v[190:193], v150 offset:50176
	global_load_lds_dwordx4 v[218:219], off
	s_add_i32 m0, s26, 0x2000
	s_add_u32 s24, s24, 0x40080
	v_lshl_add_u64 v[218:219], v[220:221], 0, s[8:9]
	s_addc_u32 s25, s25, 0
	s_add_i32 s26, s54, s28
	ds_read_b128 v[194:197], v150 offset:51200
	ds_read_b128 v[198:201], v150 offset:52224
	global_load_lds_dwordx4 v[218:219], off
	v_lshl_add_u64 v[218:219], s[24:25], 0, v[132:133]
	s_mov_b32 m0, s26
	ds_read_b128 v[202:205], v150 offset:53248
	global_load_lds_dwordx4 v[218:219], off
	v_lshl_add_u64 v[218:219], s[24:25], 0, v[128:129]
	s_add_i32 m0, s26, 0x2000
	ds_read_b128 v[206:209], v150 offset:54272
	global_load_lds_dwordx4 v[218:219], off
	v_lshl_add_u64 v[218:219], v[222:223], 0, s[8:9]
	s_mov_b32 m0, s38
	ds_read_b128 v[210:213], v150 offset:55296
	global_load_lds_dwordx4 v[218:219], off
	v_lshl_add_u64 v[218:219], v[224:225], 0, s[8:9]
	s_mov_b32 m0, s39
	ds_read_b128 v[214:217], v150 offset:56320
	global_load_lds_dwordx4 v[218:219], off
	s_cmp_lg_u32 s79, 3
	s_cbranch_scc1 .Ltr607_3_w
	s_cmp_eq_u32 s70, 0
	s_cbranch_scc1 .Ltr607_3_w
	s_cmp_eq_u32 s70, 1
	s_cbranch_scc1 .Ltr607_3_s1
	s_cmp_eq_u32 s70, 2
	s_cbranch_scc1 .Ltr607_3_s2
	s_cmp_eq_u32 s70, 3
	s_cbranch_scc1 .Ltr607_3_s3
	s_cmp_eq_u32 s70, 4
	s_cbranch_scc1 .Ltr607_3_s4
	s_cmp_eq_u32 s70, 5
	s_cbranch_scc1 .Ltr607_3_s5
	v_add_u32_e32 v255, 0xf2000, v254
	global_store_dwordx4 v255, v[250:253], s[64:65]
	s_branch .Ltr607_3_d

; __device__ __forceinline__ unsigned cvt_pk_bf16(float lo, float hi) { unsigned r; asm volatile("v_cvt_pk_bf16_f32 %0, %1, %2" : "=v"(r) : "v"(lo), "v"(hi)); return r; }
;     __device__ __forceinline__ void operator()(Acc& acc, const Unit& u, int wr, int wc, int fr, int fq) const {
;         const int row0 = u.pm * BM + wr * 64 + fr, col0 = u.pn * 128 + wc * 32 + 8 * fq;
; #pragma unroll
;         for (int ai = 0; ai < 2; ++ai)
; #pragma unroll
;             for (int m = 0; m < 4; ++m) {
;                 const int row = row0 + ai * HALF + m * 16;
;                 const float r = rs[u.idx * BM + wr * 64 + fr + ai * HALF + m * 16];
;                 const float c1 = -r * 1.4426950408889634f, r2 = r * r;
;                 f32x4 o[2];
; #pragma unroll
;                 for (int n = 0; n < 2; ++n) {
;                     const f32x4 g = acc[ai][0][m][n], up = acc[ai][1][m][n];
;                     const f32x4 t = g * c1; f32x4 e;
; #pragma unroll
;                     for (int i = 0; i < 4; ++i) e[i] = __builtin_amdgcn_exp2f(t[i]);
;                     const f32x4 d = e + 1.0f; f32x4 q;
; #pragma unroll
;                     for (int i = 0; i < 4; ++i) q[i] = __builtin_amdgcn_rcpf(d[i]);
;                     o[n] = (g * up) * (q * r2);
;                 }
;                 u32x4 w; w.x = cvt_pk_bf16(o[0][0], o[0][1]); w.y = cvt_pk_bf16(o[0][2], o[0][3]); w.z = cvt_pk_bf16(o[1][0], o[1][1]); w.w = cvt_pk_bf16(o[1][2], o[1][3]);
;                 *(u32x4*)(O + (size_t)row * DFF + col0) = w;
.Ltr607_3_j:
	s_waitcnt lgkmcnt(0)
	s_setprio 1
	s_barrier
	v_mfma_f32_16x16x32_bf16 v[60:63], v[154:157], v[186:189], v[60:63]
	v_mfma_f32_16x16x32_bf16 v[52:55], v[162:165], v[186:189], v[52:55]
	v_mfma_f32_16x16x32_bf16 v[44:47], v[154:157], v[194:197], v[44:47]
	v_mfma_f32_16x16x32_bf16 v[36:39], v[162:165], v[194:197], v[36:39]
	v_mfma_f32_16x16x32_bf16 v[28:31], v[154:157], v[202:205], v[28:31]
	v_mfma_f32_16x16x32_bf16 v[20:23], v[162:165], v[202:205], v[20:23]
	v_mfma_f32_16x16x32_bf16 v[12:15], v[154:157], v[210:213], v[12:15]
	v_mfma_f32_16x16x32_bf16 v[4:7], v[162:165], v[210:213], v[4:7]
	v_mfma_f32_16x16x32_bf16 v[60:63], v[158:161], v[190:193], v[60:63]
	v_mfma_f32_16x16x32_bf16 v[52:55], v[166:169], v[190:193], v[52:55]
	v_mfma_f32_16x16x32_bf16 v[44:47], v[158:161], v[198:201], v[44:47]
	v_mfma_f32_16x16x32_bf16 v[36:39], v[166:169], v[198:201], v[36:39]
	v_mfma_f32_16x16x32_bf16 v[28:31], v[158:161], v[206:209], v[28:31]
	v_mfma_f32_16x16x32_bf16 v[20:23], v[166:169], v[206:209], v[20:23]
	v_mfma_f32_16x16x32_bf16 v[12:15], v[158:161], v[214:217], v[12:15]
	v_mfma_f32_16x16x32_bf16 v[4:7], v[166:169], v[214:217], v[4:7]
	s_setprio 0
	s_setprio 1
	v_mfma_f32_16x16x32_bf16 v[56:59], v[170:173], v[186:189], v[56:59]
	v_mfma_f32_16x16x32_bf16 v[48:51], v[178:181], v[186:189], v[48:51]
	v_mfma_f32_16x16x32_bf16 v[40:43], v[170:173], v[194:197], v[40:43]
	v_mfma_f32_16x16x32_bf16 v[32:35], v[178:181], v[194:197], v[32:35]
	v_mfma_f32_16x16x32_bf16 v[24:27], v[170:173], v[202:205], v[24:27]
	v_mfma_f32_16x16x32_bf16 v[16:19], v[178:181], v[202:205], v[16:19]
	v_mfma_f32_16x16x32_bf16 v[8:11], v[170:173], v[210:213], v[8:11]
	v_mfma_f32_16x16x32_bf16 v[0:3], v[178:181], v[210:213], v[0:3]
	v_mfma_f32_16x16x32_bf16 v[56:59], v[174:177], v[190:193], v[56:59]
	v_mfma_f32_16x16x32_bf16 v[48:51], v[182:185], v[190:193], v[48:51]
	v_mfma_f32_16x16x32_bf16 v[40:43], v[174:177], v[198:201], v[40:43]
	v_mfma_f32_16x16x32_bf16 v[32:35], v[182:185], v[198:201], v[32:35]
	v_mfma_f32_16x16x32_bf16 v[24:27], v[174:177], v[206:209], v[24:27]
	v_mfma_f32_16x16x32_bf16 v[16:19], v[182:185], v[206:209], v[16:19]
	v_mfma_f32_16x16x32_bf16 v[8:11], v[174:177], v[214:217], v[8:11]
	v_mfma_f32_16x16x32_bf16 v[0:3], v[182:185], v[214:217], v[0:3]
	s_barrier
	s_setprio 0
	s_add_i32 s52, s52, 2
	s_add_u32 s22, s22, 0x100
	s_addc_u32 s23, s23, 0
	s_add_u32 s50, s50, 0x100
	s_addc_u32 s51, s51, 0
	s_cmp_gt_u32 s52, 13
	s_cbranch_scc0 .LBB0_607
	s_and_b64 vcc, exec, s[10:11]
	s_cbranch_vccz .LBB0_610
	s_barrier
.LBB0_610:
	v_lshl_add_u32 v154, s45, 10, v146
	ds_read_b32 v200, v154
	ds_read_b32 v201, v154 offset:64
	ds_read_b32 v202, v154 offset:128
	ds_read_b32 v203, v154 offset:192
	ds_read_b32 v204, v154 offset:512
	ds_read_b32 v205, v154 offset:576
	ds_read_b32 v206, v154 offset:640
	ds_read_b32 v207, v154 offset:704
	v_lshl_or_b32 v156, s47, 7, v147
	v_lshl_add_u32 v151, s20, 8, v144
	v_lshlrev_b32_e32 v156, 1, v156
	v_mov_b32_e32 v198, 1.0
	v_mad_u32_u24 v155, v151, s42, v156
	s_waitcnt lgkmcnt(0)
	v_mul_f32_e32 v158, 0xbfb8aa3b, v200
	v_mul_f32_e32 v160, v200, v200
	v_pk_mul_f32 v[162:163], v[124:125], v[158:159] op_sel_hi:[1,0]
	v_pk_mul_f32 v[164:165], v[126:127], v[158:159] op_sel_hi:[1,0]
	v_pk_mul_f32 v[166:167], v[116:117], v[158:159] op_sel_hi:[1,0]
	v_pk_mul_f32 v[168:169], v[118:119], v[158:159] op_sel_hi:[1,0]
	v_exp_f32_e32 v162, v162
	v_exp_f32_e32 v163, v163
	v_pk_mul_f32 v[120:121], v[124:125], v[120:121]
	v_exp_f32_e32 v164, v164
	v_exp_f32_e32 v165, v165
	v_pk_mul_f32 v[122:123], v[126:127], v[122:123]
	v_exp_f32_e32 v166, v166
	v_exp_f32_e32 v167, v167
	v_pk_mul_f32 v[112:113], v[116:117], v[112:113]
	v_exp_f32_e32 v168, v168
	v_exp_f32_e32 v169, v169
	v_pk_mul_f32 v[114:115], v[118:119], v[114:115]
	v_pk_add_f32 v[162:163], v[162:163], v[198:199] op_sel_hi:[1,0]
	v_pk_add_f32 v[164:165], v[164:165], v[198:199] op_sel_hi:[1,0]
	v_pk_add_f32 v[166:167], v[166:167], v[198:199] op_sel_hi:[1,0]
	v_pk_add_f32 v[168:169], v[168:169], v[198:199] op_sel_hi:[1,0]
	v_rcp_f32_e32 v162, v162
	v_rcp_f32_e32 v163, v163
	v_rcp_f32_e32 v164, v164
	v_rcp_f32_e32 v165, v165
	v_rcp_f32_e32 v166, v166
	v_rcp_f32_e32 v167, v167
	v_rcp_f32_e32 v168, v168
	v_rcp_f32_e32 v169, v169
	v_pk_mul_f32 v[162:163], v[160:161], v[162:163] op_sel_hi:[0,1]
	v_pk_mul_f32 v[164:165], v[160:161], v[164:165] op_sel_hi:[0,1]
	v_pk_mul_f32 v[166:167], v[160:161], v[166:167] op_sel_hi:[0,1]
	v_pk_mul_f32 v[168:169], v[160:161], v[168:169] op_sel_hi:[0,1]
	v_pk_mul_f32 v[120:121], v[120:121], v[162:163]
	v_pk_mul_f32 v[122:123], v[122:123], v[164:165]
	v_pk_mul_f32 v[112:113], v[112:113], v[166:167]
	v_pk_mul_f32 v[114:115], v[114:115], v[168:169]
	v_cvt_pk_bf16_f32 v170, v120, v121
	v_cvt_pk_bf16_f32 v171, v122, v123
	v_cvt_pk_bf16_f32 v172, v112, v113
	v_cvt_pk_bf16_f32 v173, v114, v115
	global_store_dwordx4 v155, v[170:173], s[64:65]
	v_mul_f32_e32 v158, 0xbfb8aa3b, v201
	v_mul_f32_e32 v160, v201, v201
	v_pk_mul_f32 v[162:163], v[108:109], v[158:159] op_sel_hi:[1,0]
	v_pk_mul_f32 v[164:165], v[110:111], v[158:159] op_sel_hi:[1,0]
	v_pk_mul_f32 v[166:167], v[100:101], v[158:159] op_sel_hi:[1,0]
	v_pk_mul_f32 v[168:169], v[102:103], v[158:159] op_sel_hi:[1,0]
	v_exp_f32_e32 v162, v162
	v_exp_f32_e32 v163, v163
	v_pk_mul_f32 v[104:105], v[108:109], v[104:105]
	v_exp_f32_e32 v164, v164
	v_exp_f32_e32 v165, v165
	v_pk_mul_f32 v[106:107], v[110:111], v[106:107]
	v_exp_f32_e32 v166, v166
	v_exp_f32_e32 v167, v167
	v_pk_mul_f32 v[96:97], v[100:101], v[96:97]
	v_exp_f32_e32 v168, v168
	v_exp_f32_e32 v169, v169
	v_pk_mul_f32 v[98:99], v[102:103], v[98:99]
; __device__ __forceinline__ unsigned cvt_pk_bf16(float lo, float hi) { unsigned r; asm volatile("v_cvt_pk_bf16_f32 %0, %1, %2" : "=v"(r) : "v"(lo), "v"(hi)); return r; }
;     __device__ __forceinline__ void operator()(Acc& acc, const Unit& u, int wr, int wc, int fr, int fq) const {
;     ...
;             for (int m = 0; m < 4; ++m) {
;                 const int row = row0 + ai * HALF + m * 16;
;                 const float r = rs[u.idx * BM + wr * 64 + fr + ai * HALF + m * 16];
;                 const float c1 = -r * 1.4426950408889634f, r2 = r * r;
;                 f32x4 o[2];
; #pragma unroll
;                 for (int n = 0; n < 2; ++n) {
;                     const f32x4 g = acc[ai][0][m][n], up = acc[ai][1][m][n];
;                     const f32x4 t = g * c1; f32x4 e;
; #pragma unroll
;                     for (int i = 0; i < 4; ++i) e[i] = __builtin_amdgcn_exp2f(t[i]);
;                     const f32x4 d = e + 1.0f; f32x4 q;
; #pragma unroll
;                     for (int i = 0; i < 4; ++i) q[i] = __builtin_amdgcn_rcpf(d[i]);
;                     o[n] = (g * up) * (q * r2);
;                 }
;                 u32x4 w; w.x = cvt_pk_bf16(o[0][0], o[0][1]); w.y = cvt_pk_bf16(o[0][2], o[0][3]); w.z = cvt_pk_bf16(o[1][0], o[1][1]); w.w = cvt_pk_bf16(o[1][2], o[1][3]);
;                 *(u32x4*)(O + (size_t)row * DFF + col0) = w;
	v_pk_add_f32 v[162:163], v[162:163], v[198:199] op_sel_hi:[1,0]
	v_pk_add_f32 v[164:165], v[164:165], v[198:199] op_sel_hi:[1,0]
	v_pk_add_f32 v[166:167], v[166:167], v[198:199] op_sel_hi:[1,0]
	v_pk_add_f32 v[168:169], v[168:169], v[198:199] op_sel_hi:[1,0]
	v_rcp_f32_e32 v162, v162
	v_rcp_f32_e32 v163, v163
	v_rcp_f32_e32 v164, v164
	v_rcp_f32_e32 v165, v165
	v_rcp_f32_e32 v166, v166
	v_rcp_f32_e32 v167, v167
	v_rcp_f32_e32 v168, v168
	v_rcp_f32_e32 v169, v169
	v_pk_mul_f32 v[162:163], v[160:161], v[162:163] op_sel_hi:[0,1]
	v_pk_mul_f32 v[164:165], v[160:161], v[164:165] op_sel_hi:[0,1]
	v_pk_mul_f32 v[166:167], v[160:161], v[166:167] op_sel_hi:[0,1]
	v_pk_mul_f32 v[168:169], v[160:161], v[168:169] op_sel_hi:[0,1]
	v_pk_mul_f32 v[104:105], v[104:105], v[162:163]
	v_pk_mul_f32 v[106:107], v[106:107], v[164:165]
	v_pk_mul_f32 v[96:97], v[96:97], v[166:167]
	v_pk_mul_f32 v[98:99], v[98:99], v[168:169]
	v_cvt_pk_bf16_f32 v176, v104, v105
	v_cvt_pk_bf16_f32 v177, v106, v107
	v_cvt_pk_bf16_f32 v178, v96, v97
	v_cvt_pk_bf16_f32 v179, v98, v99
	v_add_u32_e32 v175, 0x16000, v155
	global_store_dwordx4 v175, v[176:179], s[64:65]
	v_mul_f32_e32 v158, 0xbfb8aa3b, v202
	v_mul_f32_e32 v160, v202, v202
	v_pk_mul_f32 v[162:163], v[92:93], v[158:159] op_sel_hi:[1,0]
	v_pk_mul_f32 v[164:165], v[94:95], v[158:159] op_sel_hi:[1,0]
	v_pk_mul_f32 v[166:167], v[84:85], v[158:159] op_sel_hi:[1,0]
	v_pk_mul_f32 v[168:169], v[86:87], v[158:159] op_sel_hi:[1,0]
	v_exp_f32_e32 v162, v162
	v_exp_f32_e32 v163, v163
	v_pk_mul_f32 v[88:89], v[92:93], v[88:89]
	v_exp_f32_e32 v164, v164
	v_exp_f32_e32 v165, v165
	v_pk_mul_f32 v[90:91], v[94:95], v[90:91]
	v_exp_f32_e32 v166, v166
	v_exp_f32_e32 v167, v167
	v_pk_mul_f32 v[80:81], v[84:85], v[80:81]
	v_exp_f32_e32 v168, v168
	v_exp_f32_e32 v169, v169
	v_pk_mul_f32 v[82:83], v[86:87], v[82:83]
	v_pk_add_f32 v[162:163], v[162:163], v[198:199] op_sel_hi:[1,0]
	v_pk_add_f32 v[164:165], v[164:165], v[198:199] op_sel_hi:[1,0]
	v_pk_add_f32 v[166:167], v[166:167], v[198:199] op_sel_hi:[1,0]
	v_pk_add_f32 v[168:169], v[168:169], v[198:199] op_sel_hi:[1,0]
	v_rcp_f32_e32 v162, v162
	v_rcp_f32_e32 v163, v163
	v_rcp_f32_e32 v164, v164
	v_rcp_f32_e32 v165, v165
	v_rcp_f32_e32 v166, v166
	v_rcp_f32_e32 v167, v167
	v_rcp_f32_e32 v168, v168
	v_rcp_f32_e32 v169, v169
	v_pk_mul_f32 v[162:163], v[160:161], v[162:163] op_sel_hi:[0,1]
	v_pk_mul_f32 v[164:165], v[160:161], v[164:165] op_sel_hi:[0,1]
	v_pk_mul_f32 v[166:167], v[160:161], v[166:167] op_sel_hi:[0,1]
	v_pk_mul_f32 v[168:169], v[160:161], v[168:169] op_sel_hi:[0,1]
	v_pk_mul_f32 v[88:89], v[88:89], v[162:163]
	v_pk_mul_f32 v[90:91], v[90:91], v[164:165]
	v_pk_mul_f32 v[80:81], v[80:81], v[166:167]
	v_pk_mul_f32 v[82:83], v[82:83], v[168:169]
	v_cvt_pk_bf16_f32 v228, v88, v89
	v_cvt_pk_bf16_f32 v229, v90, v91
	v_cvt_pk_bf16_f32 v230, v80, v81
	v_cvt_pk_bf16_f32 v231, v82, v83
	v_mul_f32_e32 v158, 0xbfb8aa3b, v203
	v_mul_f32_e32 v160, v203, v203
	v_pk_mul_f32 v[162:163], v[76:77], v[158:159] op_sel_hi:[1,0]
	v_pk_mul_f32 v[164:165], v[78:79], v[158:159] op_sel_hi:[1,0]
	v_pk_mul_f32 v[166:167], v[68:69], v[158:159] op_sel_hi:[1,0]
	v_pk_mul_f32 v[168:169], v[70:71], v[158:159] op_sel_hi:[1,0]
	v_exp_f32_e32 v162, v162
	v_exp_f32_e32 v163, v163
	v_pk_mul_f32 v[72:73], v[76:77], v[72:73]
	v_exp_f32_e32 v164, v164
	v_exp_f32_e32 v165, v165
	v_pk_mul_f32 v[74:75], v[78:79], v[74:75]
	v_exp_f32_e32 v166, v166
	v_exp_f32_e32 v167, v167
	v_pk_mul_f32 v[64:65], v[68:69], v[64:65]
	v_exp_f32_e32 v168, v168
	v_exp_f32_e32 v169, v169
	v_pk_mul_f32 v[66:67], v[70:71], v[66:67]
	v_pk_add_f32 v[162:163], v[162:163], v[198:199] op_sel_hi:[1,0]
	v_pk_add_f32 v[164:165], v[164:165], v[198:199] op_sel_hi:[1,0]
	v_pk_add_f32 v[166:167], v[166:167], v[198:199] op_sel_hi:[1,0]
	v_pk_add_f32 v[168:169], v[168:169], v[198:199] op_sel_hi:[1,0]
	v_rcp_f32_e32 v162, v162
	v_rcp_f32_e32 v163, v163
	v_rcp_f32_e32 v164, v164
	v_rcp_f32_e32 v165, v165
	v_rcp_f32_e32 v166, v166
	v_rcp_f32_e32 v167, v167
	v_rcp_f32_e32 v168, v168
	v_rcp_f32_e32 v169, v169
	v_pk_mul_f32 v[162:163], v[160:161], v[162:163] op_sel_hi:[0,1]
	v_pk_mul_f32 v[164:165], v[160:161], v[164:165] op_sel_hi:[0,1]
	v_pk_mul_f32 v[166:167], v[160:161], v[166:167] op_sel_hi:[0,1]
	v_pk_mul_f32 v[168:169], v[160:161], v[168:169] op_sel_hi:[0,1]
	v_pk_mul_f32 v[72:73], v[72:73], v[162:163]
	v_pk_mul_f32 v[74:75], v[74:75], v[164:165]
	v_pk_mul_f32 v[64:65], v[64:65], v[166:167]
	v_pk_mul_f32 v[66:67], v[66:67], v[168:169]
	v_cvt_pk_bf16_f32 v232, v72, v73
	v_cvt_pk_bf16_f32 v233, v74, v75
	v_cvt_pk_bf16_f32 v234, v64, v65
	v_cvt_pk_bf16_f32 v235, v66, v67
	v_mul_f32_e32 v158, 0xbfb8aa3b, v204
	v_mul_f32_e32 v160, v204, v204
	v_pk_mul_f32 v[162:163], v[60:61], v[158:159] op_sel_hi:[1,0]
	v_pk_mul_f32 v[164:165], v[62:63], v[158:159] op_sel_hi:[1,0]
	v_pk_mul_f32 v[166:167], v[52:53], v[158:159] op_sel_hi:[1,0]
	v_pk_mul_f32 v[168:169], v[54:55], v[158:159] op_sel_hi:[1,0]
	v_exp_f32_e32 v162, v162
	v_exp_f32_e32 v163, v163
	v_pk_mul_f32 v[56:57], v[60:61], v[56:57]
	v_exp_f32_e32 v164, v164
	v_exp_f32_e32 v165, v165
	v_pk_mul_f32 v[58:59], v[62:63], v[58:59]
	v_exp_f32_e32 v166, v166
	v_exp_f32_e32 v167, v167
	v_pk_mul_f32 v[48:49], v[52:53], v[48:49]
	v_exp_f32_e32 v168, v168
	v_exp_f32_e32 v169, v169
	v_pk_mul_f32 v[50:51], v[54:55], v[50:51]
	v_pk_add_f32 v[162:163], v[162:163], v[198:199] op_sel_hi:[1,0]
	v_pk_add_f32 v[164:165], v[164:165], v[198:199] op_sel_hi:[1,0]
	v_pk_add_f32 v[166:167], v[166:167], v[198:199] op_sel_hi:[1,0]
	v_pk_add_f32 v[168:169], v[168:169], v[198:199] op_sel_hi:[1,0]
	v_rcp_f32_e32 v162, v162
	v_rcp_f32_e32 v163, v163
; __device__ __forceinline__ unsigned cvt_pk_bf16(float lo, float hi) { unsigned r; asm volatile("v_cvt_pk_bf16_f32 %0, %1, %2" : "=v"(r) : "v"(lo), "v"(hi)); return r; }
; #define PG8_BAR __builtin_amdgcn_s_barrier()
;     __device__ __forceinline__ void operator()(Acc& acc, const Unit& u, int wr, int wc, int fr, int fq) const {
;     ...
;                     const f32x4 g = acc[ai][0][m][n], up = acc[ai][1][m][n];
;                     const f32x4 t = g * c1; f32x4 e;
; #pragma unroll
;                     for (int i = 0; i < 4; ++i) e[i] = __builtin_amdgcn_exp2f(t[i]);
;                     const f32x4 d = e + 1.0f; f32x4 q;
; #pragma unroll
;                     for (int i = 0; i < 4; ++i) q[i] = __builtin_amdgcn_rcpf(d[i]);
;                     o[n] = (g * up) * (q * r2);
;                 }
;                 u32x4 w; w.x = cvt_pk_bf16(o[0][0], o[0][1]); w.y = cvt_pk_bf16(o[0][2], o[0][3]); w.z = cvt_pk_bf16(o[1][0], o[1][1]); w.w = cvt_pk_bf16(o[1][2], o[1][3]);
;                 *(u32x4*)(O + (size_t)row * DFF + col0) = w;
; template <class Epi, class Sched, bool ALIGN_EPI>
; __device__ __forceinline__ void gemm_phase(LAS unsigned char* lds, const Gemm g, const Sched& S, const Epi& E) {
;     ...
;         E(acc, cur, wr, wc, fr, fq);
;         if (!has_next) break;
; #pragma unroll
;         for (int a = 0; a < 2; ++a)
; #pragma unroll
;             for (int b = 0; b < 2; ++b)
; #pragma unroll
;                 for (int m = 0; m < 4; ++m)
; #pragma unroll
;                     for (int n = 0; n < 2; ++n) acc[a][b][m][n] = (f32x4){0.f, 0.f, 0.f, 0.f};
;         cur = nxt; cA = nA; cB = nB; ++ui;
;         if constexpr (ALIGN_EPI) { if (wr == 1) PG8_BAR; }
	v_rcp_f32_e32 v164, v164
	v_rcp_f32_e32 v165, v165
	v_rcp_f32_e32 v166, v166
	v_rcp_f32_e32 v167, v167
	v_rcp_f32_e32 v168, v168
	v_rcp_f32_e32 v169, v169
	v_pk_mul_f32 v[162:163], v[160:161], v[162:163] op_sel_hi:[0,1]
	v_pk_mul_f32 v[164:165], v[160:161], v[164:165] op_sel_hi:[0,1]
	v_pk_mul_f32 v[166:167], v[160:161], v[166:167] op_sel_hi:[0,1]
	v_pk_mul_f32 v[168:169], v[160:161], v[168:169] op_sel_hi:[0,1]
	v_pk_mul_f32 v[56:57], v[56:57], v[162:163]
	v_pk_mul_f32 v[58:59], v[58:59], v[164:165]
	v_pk_mul_f32 v[48:49], v[48:49], v[166:167]
	v_pk_mul_f32 v[50:51], v[50:51], v[168:169]
	v_cvt_pk_bf16_f32 v236, v56, v57
	v_cvt_pk_bf16_f32 v237, v58, v59
	v_cvt_pk_bf16_f32 v238, v48, v49
	v_cvt_pk_bf16_f32 v239, v50, v51
	v_mul_f32_e32 v158, 0xbfb8aa3b, v205
	v_mul_f32_e32 v160, v205, v205
	v_pk_mul_f32 v[162:163], v[44:45], v[158:159] op_sel_hi:[1,0]
	v_pk_mul_f32 v[164:165], v[46:47], v[158:159] op_sel_hi:[1,0]
	v_pk_mul_f32 v[166:167], v[36:37], v[158:159] op_sel_hi:[1,0]
	v_pk_mul_f32 v[168:169], v[38:39], v[158:159] op_sel_hi:[1,0]
	v_exp_f32_e32 v162, v162
	v_exp_f32_e32 v163, v163
	v_pk_mul_f32 v[40:41], v[44:45], v[40:41]
	v_exp_f32_e32 v164, v164
	v_exp_f32_e32 v165, v165
	v_pk_mul_f32 v[42:43], v[46:47], v[42:43]
	v_exp_f32_e32 v166, v166
	v_exp_f32_e32 v167, v167
	v_pk_mul_f32 v[32:33], v[36:37], v[32:33]
	v_exp_f32_e32 v168, v168
	v_exp_f32_e32 v169, v169
	v_pk_mul_f32 v[34:35], v[38:39], v[34:35]
	v_pk_add_f32 v[162:163], v[162:163], v[198:199] op_sel_hi:[1,0]
	v_pk_add_f32 v[164:165], v[164:165], v[198:199] op_sel_hi:[1,0]
	v_pk_add_f32 v[166:167], v[166:167], v[198:199] op_sel_hi:[1,0]
	v_pk_add_f32 v[168:169], v[168:169], v[198:199] op_sel_hi:[1,0]
	v_rcp_f32_e32 v162, v162
	v_rcp_f32_e32 v163, v163
	v_rcp_f32_e32 v164, v164
	v_rcp_f32_e32 v165, v165
	v_rcp_f32_e32 v166, v166
	v_rcp_f32_e32 v167, v167
	v_rcp_f32_e32 v168, v168
	v_rcp_f32_e32 v169, v169
	v_pk_mul_f32 v[162:163], v[160:161], v[162:163] op_sel_hi:[0,1]
	v_pk_mul_f32 v[164:165], v[160:161], v[164:165] op_sel_hi:[0,1]
	v_pk_mul_f32 v[166:167], v[160:161], v[166:167] op_sel_hi:[0,1]
	v_pk_mul_f32 v[168:169], v[160:161], v[168:169] op_sel_hi:[0,1]
	v_pk_mul_f32 v[40:41], v[40:41], v[162:163]
	v_pk_mul_f32 v[42:43], v[42:43], v[164:165]
	v_pk_mul_f32 v[32:33], v[32:33], v[166:167]
	v_pk_mul_f32 v[34:35], v[34:35], v[168:169]
	v_cvt_pk_bf16_f32 v240, v40, v41
	v_cvt_pk_bf16_f32 v241, v42, v43
	v_cvt_pk_bf16_f32 v242, v32, v33
	v_cvt_pk_bf16_f32 v243, v34, v35
	v_mul_f32_e32 v158, 0xbfb8aa3b, v206
	v_mul_f32_e32 v160, v206, v206
	v_pk_mul_f32 v[162:163], v[28:29], v[158:159] op_sel_hi:[1,0]
	v_pk_mul_f32 v[164:165], v[30:31], v[158:159] op_sel_hi:[1,0]
	v_pk_mul_f32 v[166:167], v[20:21], v[158:159] op_sel_hi:[1,0]
	v_pk_mul_f32 v[168:169], v[22:23], v[158:159] op_sel_hi:[1,0]
	v_exp_f32_e32 v162, v162
	v_exp_f32_e32 v163, v163
	v_pk_mul_f32 v[24:25], v[28:29], v[24:25]
	v_exp_f32_e32 v164, v164
	v_exp_f32_e32 v165, v165
	v_pk_mul_f32 v[26:27], v[30:31], v[26:27]
	v_exp_f32_e32 v166, v166
	v_exp_f32_e32 v167, v167
	v_pk_mul_f32 v[16:17], v[20:21], v[16:17]
	v_exp_f32_e32 v168, v168
	v_exp_f32_e32 v169, v169
	v_pk_mul_f32 v[18:19], v[22:23], v[18:19]
	v_pk_add_f32 v[162:163], v[162:163], v[198:199] op_sel_hi:[1,0]
	v_pk_add_f32 v[164:165], v[164:165], v[198:199] op_sel_hi:[1,0]
	v_pk_add_f32 v[166:167], v[166:167], v[198:199] op_sel_hi:[1,0]
	v_pk_add_f32 v[168:169], v[168:169], v[198:199] op_sel_hi:[1,0]
	v_rcp_f32_e32 v162, v162
	v_rcp_f32_e32 v163, v163
	v_rcp_f32_e32 v164, v164
	v_rcp_f32_e32 v165, v165
	v_rcp_f32_e32 v166, v166
	v_rcp_f32_e32 v167, v167
	v_rcp_f32_e32 v168, v168
	v_rcp_f32_e32 v169, v169
	v_pk_mul_f32 v[162:163], v[160:161], v[162:163] op_sel_hi:[0,1]
	v_pk_mul_f32 v[164:165], v[160:161], v[164:165] op_sel_hi:[0,1]
	v_pk_mul_f32 v[166:167], v[160:161], v[166:167] op_sel_hi:[0,1]
	v_pk_mul_f32 v[168:169], v[160:161], v[168:169] op_sel_hi:[0,1]
	v_pk_mul_f32 v[24:25], v[24:25], v[162:163]
	v_pk_mul_f32 v[26:27], v[26:27], v[164:165]
	v_pk_mul_f32 v[16:17], v[16:17], v[166:167]
	v_pk_mul_f32 v[18:19], v[18:19], v[168:169]
	v_cvt_pk_bf16_f32 v246, v24, v25
	v_cvt_pk_bf16_f32 v247, v26, v27
	v_cvt_pk_bf16_f32 v248, v16, v17
	v_cvt_pk_bf16_f32 v249, v18, v19
	v_mul_f32_e32 v158, 0xbfb8aa3b, v207
	v_mul_f32_e32 v160, v207, v207
	v_pk_mul_f32 v[162:163], v[12:13], v[158:159] op_sel_hi:[1,0]
	v_pk_mul_f32 v[164:165], v[14:15], v[158:159] op_sel_hi:[1,0]
	v_pk_mul_f32 v[166:167], v[4:5], v[158:159] op_sel_hi:[1,0]
	v_pk_mul_f32 v[168:169], v[6:7], v[158:159] op_sel_hi:[1,0]
	v_exp_f32_e32 v162, v162
	v_exp_f32_e32 v163, v163
	v_pk_mul_f32 v[8:9], v[12:13], v[8:9]
	v_exp_f32_e32 v164, v164
	v_exp_f32_e32 v165, v165
	v_pk_mul_f32 v[10:11], v[14:15], v[10:11]
	v_exp_f32_e32 v166, v166
	v_exp_f32_e32 v167, v167
	v_pk_mul_f32 v[0:1], v[4:5], v[0:1]
	v_exp_f32_e32 v168, v168
	v_exp_f32_e32 v169, v169
	v_pk_mul_f32 v[2:3], v[6:7], v[2:3]
	v_pk_add_f32 v[162:163], v[162:163], v[198:199] op_sel_hi:[1,0]
	v_pk_add_f32 v[164:165], v[164:165], v[198:199] op_sel_hi:[1,0]
	v_pk_add_f32 v[166:167], v[166:167], v[198:199] op_sel_hi:[1,0]
	v_pk_add_f32 v[168:169], v[168:169], v[198:199] op_sel_hi:[1,0]
	v_rcp_f32_e32 v162, v162
	v_rcp_f32_e32 v163, v163
	v_rcp_f32_e32 v164, v164
	v_rcp_f32_e32 v165, v165
	v_rcp_f32_e32 v166, v166
	v_rcp_f32_e32 v167, v167
	v_rcp_f32_e32 v168, v168
	v_rcp_f32_e32 v169, v169
	v_pk_mul_f32 v[162:163], v[160:161], v[162:163] op_sel_hi:[0,1]
	v_pk_mul_f32 v[164:165], v[160:161], v[164:165] op_sel_hi:[0,1]
	v_pk_mul_f32 v[166:167], v[160:161], v[166:167] op_sel_hi:[0,1]
	v_pk_mul_f32 v[168:169], v[160:161], v[168:169] op_sel_hi:[0,1]
	v_pk_mul_f32 v[8:9], v[8:9], v[162:163]
	v_pk_mul_f32 v[10:11], v[10:11], v[164:165]
	v_pk_mul_f32 v[0:1], v[0:1], v[166:167]
	v_pk_mul_f32 v[2:3], v[2:3], v[168:169]
	v_cvt_pk_bf16_f32 v250, v8, v9
	v_cvt_pk_bf16_f32 v251, v10, v11
	v_cvt_pk_bf16_f32 v252, v0, v1
	v_cvt_pk_bf16_f32 v253, v2, v3
	v_mov_b32_e32 v254, v155
	s_andn2_b64 vcc, exec, s[2:3]
	s_mov_b64 s[2:3], -1
	s_mov_b32 s101, 1
	s_mov_b32 s70, 1
	s_cbranch_vccz .Lswg_def_607
	s_mov_b32 s70, 0
	v_add_u32_e32 v255, 0x2c000, v254
	global_store_dwordx4 v255, v[228:231], s[64:65]
	v_add_u32_e32 v244, 0x42000, v254
	global_store_dwordx4 v244, v[232:235], s[64:65]
	v_add_u32_e32 v255, 0xb0000, v254
	global_store_dwordx4 v255, v[236:239], s[64:65]
	v_add_u32_e32 v244, 0xc6000, v254
	global_store_dwordx4 v244, v[240:243], s[64:65]
	v_add_u32_e32 v255, 0xdc000, v254
	global_store_dwordx4 v255, v[246:249], s[64:65]
	v_add_u32_e32 v244, 0xf2000, v254
	global_store_dwordx4 v244, v[250:253], s[64:65]
	s_branch .LBB0_603

; #define PG8_STAGE(bufoff, gbase, voff) do { _Pragma("unroll") for (int _i = 0; _i < 2; ++_i) \
;         __builtin_amdgcn_global_load_lds((const unsigned*)((const char*)(gbase) + (voff)[_i]), (LAS unsigned*)(lds + (bufoff) + ldsw + _i * 8192), 16, 0, 0); } while (0)
; #define PG8_WAIT_V(n) asm volatile("s_waitcnt vmcnt(" #n ")" ::: "memory")
; #define PG8_BAR __builtin_amdgcn_s_barrier()
; template <class Epi, class Sched, bool ALIGN_EPI>
; __device__ __forceinline__ void gemm_phase(LAS unsigned char* lds, const Gemm g, const Sched& S, const Epi& E) {
;     ...
;     const char* cA = (const char*)g.A + (size_t)cur.pm * tstepA; const char* cB = (const char*)g.Bt + (size_t)cur.pn * tstepB;
;     PG8_STAGE(PG8_SB(0, 0), cB, voffB); PG8_STAGE(PG8_SB(0, 1), cB + hstepB, voffB); PG8_STAGE(PG8_SA(0, 0), cA, voffA); PG8_STAGE(PG8_SA(0, 1), cA + hstepA, voffA);
;     if (wr == 1) PG8_BAR;
;     PG8_WAIT_V(2); PG8_BAR;
;     PG8_STAGE(PG8_SB(1, 0), cB + kstep, voffB); PG8_STAGE(PG8_SA(1, 0), cA + kstep, voffA); PG8_STAGE(PG8_SB(1, 1), cB + hstepB + kstep, voffB);
;     PG8_WAIT_V(6); PG8_BAR;
.LBB0_1607:
	s_lshl_b32 s6, s6, 5
	s_and_b32 s12, s6, 0x60
	s_mov_b64 s[6:7], 0x80
	s_add_i32 m0, s19, 0x18000
	v_lshl_add_u64 v[6:7], v[6:7], 0, s[6:7]
	s_lshl_b32 s9, s8, 13
	s_lshl_b32 s13, s12, 7
	global_load_lds_dwordx4 v[6:7], off
	v_lshl_add_u64 v[4:5], v[4:5], 0, s[6:7]
	s_add_i32 m0, s19, 0x1a000
	s_add_i32 s36, s19, 0x8000
	s_add_i32 s37, s19, 0xa000
	global_load_lds_dwordx4 v[4:5], off
	v_lshl_add_u64 v[0:1], v[0:1], 0, s[6:7]
	s_mov_b32 m0, s36
	s_add_u32 s10, s22, 0x40080
	global_load_lds_dwordx4 v[0:1], off
	v_lshl_add_u64 v[0:1], v[2:3], 0, s[6:7]
	s_mov_b32 m0, s37
	s_addc_u32 s11, s23, 0
	global_load_lds_dwordx4 v[0:1], off
	s_add_i32 m0, s19, 0x1c000
	v_lshl_add_u64 v[0:1], s[10:11], 0, v[132:133]
	global_load_lds_dwordx4 v[0:1], off
	v_lshl_add_u64 v[0:1], s[10:11], 0, v[128:129]
	s_add_i32 m0, s19, 0x1e000
	s_sext_i32_i8 s44, s2
	global_load_lds_dwordx4 v[0:1], off
	s_waitcnt vmcnt(8)
	s_barrier
	v_and_b32_e32 v0, 15, v153
	v_lshlrev_b32_e32 v1, 1, v11
	v_lshl_or_b32 v144, s8, 6, v0
	v_lshl_or_b32 v2, v0, 6, v1
	v_lshlrev_b32_e32 v0, 2, v0
	v_and_b32_e32 v3, 32, v0
	v_bitop3_b32 v2, v2, s9, v3 bitop3:0xde
	v_lshlrev_b32_e32 v3, 6, v153
	s_movk_i32 s2, 0x3c0
	v_and_or_b32 v1, v3, s2, v1
	s_lshl_b32 s2, s8, 8
	s_add_i32 s2, s2, 0
	v_lshlrev_b32_e32 v3, 2, v153
	s_add_i32 s2, s2, 0x20000
	v_and_b32_e32 v3, 32, v3
	v_add_u32_e32 v146, s2, v0
	v_lshlrev_b32_e32 v0, 8, v153
	v_bitop3_b32 v145, s13, v1, v3 bitop3:0xf6
	v_and_b32_e32 v0, 0x38000, v0
	v_lshlrev_b32_e32 v1, 11, v12
	v_or3_b32 v0, v9, v0, v1
	v_add_u32_e32 v136, v0, v10
	v_lshlrev_b32_e32 v0, 4, v8
	s_waitcnt vmcnt(6)
	s_cmpk_lt_u32 s3, 0x100
	v_and_b32_e32 v0, 0x78000, v0
	s_cselect_b64 s[8:9], -1, 0
	v_or3_b32 v0, v9, v0, v1
	s_add_i32 s38, 0, 0x10000
	s_add_i32 s39, 0, 0x14000
	v_or_b32_e32 v147, s12, v11
	v_mov_b32_e32 v137, v133
	v_add_u32_e32 v138, v0, v10
	v_mov_b32_e32 v139, v133
	v_mov_b64_e32 v[140:141], 0xb00
	v_mov_b64_e32 v[142:143], 0xaff
	v_add_u32_e32 v148, s38, v145
	v_add_u32_e32 v149, s39, v145
	v_add_u32_e32 v150, 0, v2
	s_movk_i32 s40, 0x1600
	s_mov_b32 s41, 0
	s_barrier
	s_mov_b32 s70, 0
	s_mov_b32 s71, 0
	v_readlane_b32 s79, v245, 0
	s_nop 1
	s_and_b32 s79, s79, 3
	s_branch .LBB0_1610

.LBB0_1613:
	ds_read_b128 v[154:157], v148
	ds_read_b128 v[158:161], v148 offset:1024
	ds_read_b128 v[162:165], v148 offset:2048
	ds_read_b128 v[166:169], v148 offset:3072
	ds_read_b128 v[170:173], v149
	ds_read_b128 v[174:177], v149 offset:1024
	ds_read_b128 v[178:181], v149 offset:2048
	ds_read_b128 v[182:185], v149 offset:3072
	s_add_u32 s22, s20, 0xfffc0080
	s_addc_u32 s23, s21, -1
	s_cmp_eq_u32 s49, 12
	s_cselect_b32 s25, s13, s23
	s_cselect_b32 s24, s45, s22
	s_cselect_b32 s23, s11, s48
	s_cselect_b32 s22, s46, s47
	v_lshl_add_u64 v[218:219], s[20:21], 0, v[136:137]
	s_add_i32 m0, s19, 0xc000
	ds_read_b128 v[186:189], v150
	ds_read_b128 v[190:193], v150 offset:1024
	ds_read_b128 v[194:197], v150 offset:2048
	ds_read_b128 v[198:201], v150 offset:3072
	ds_read_b128 v[202:205], v150 offset:4096
	ds_read_b128 v[206:209], v150 offset:5120
	ds_read_b128 v[210:213], v150 offset:6144
	ds_read_b128 v[214:217], v150 offset:7168
	global_load_lds_dwordx4 v[218:219], off
	v_lshl_add_u64 v[218:219], s[20:21], 0, v[138:139]
	s_add_i32 m0, s19, 0xe000
	s_nop 0
	global_load_lds_dwordx4 v[218:219], off
	s_cmp_lg_u32 s79, 0
	s_cbranch_scc1 .Ltr1613_0_w
	s_cmp_eq_u32 s70, 0
	s_cbranch_scc1 .Ltr1613_0_w
	s_cmp_eq_u32 s70, 1
	s_cbranch_scc1 .Ltr1613_0_s1
	s_cmp_eq_u32 s70, 2
	s_cbranch_scc1 .Ltr1613_0_s2
	s_cmp_eq_u32 s70, 3
	s_cbranch_scc1 .Ltr1613_0_s3
	s_cmp_eq_u32 s70, 4
	s_cbranch_scc1 .Ltr1613_0_s4
	s_cmp_eq_u32 s70, 5
	s_cbranch_scc1 .Ltr1613_0_s5
	v_add_u32_e32 v255, 0xf2000, v254
	global_store_dwordx4 v255, v[250:253], s[64:65]
	s_branch .Ltr1613_0_d

.Ltr1613_0_j:
	s_waitcnt lgkmcnt(0)
	s_setprio 1
	s_barrier
	v_mfma_f32_16x16x32_bf16 v[124:127], v[154:157], v[186:189], v[124:127]
	v_mfma_f32_16x16x32_bf16 v[116:119], v[162:165], v[186:189], v[116:119]
	v_mfma_f32_16x16x32_bf16 v[108:111], v[154:157], v[194:197], v[108:111]
	v_mfma_f32_16x16x32_bf16 v[100:103], v[162:165], v[194:197], v[100:103]
	v_mfma_f32_16x16x32_bf16 v[92:95], v[154:157], v[202:205], v[92:95]
	v_mfma_f32_16x16x32_bf16 v[84:87], v[162:165], v[202:205], v[84:87]
	v_mfma_f32_16x16x32_bf16 v[76:79], v[154:157], v[210:213], v[76:79]
	v_mfma_f32_16x16x32_bf16 v[68:71], v[162:165], v[210:213], v[68:71]
	v_mfma_f32_16x16x32_bf16 v[124:127], v[158:161], v[190:193], v[124:127]
	v_mfma_f32_16x16x32_bf16 v[116:119], v[166:169], v[190:193], v[116:119]
	v_mfma_f32_16x16x32_bf16 v[108:111], v[158:161], v[198:201], v[108:111]
	v_mfma_f32_16x16x32_bf16 v[100:103], v[166:169], v[198:201], v[100:103]
	v_mfma_f32_16x16x32_bf16 v[92:95], v[158:161], v[206:209], v[92:95]
	v_mfma_f32_16x16x32_bf16 v[84:87], v[166:169], v[206:209], v[84:87]
	v_mfma_f32_16x16x32_bf16 v[76:79], v[158:161], v[214:217], v[76:79]
	v_mfma_f32_16x16x32_bf16 v[68:71], v[166:169], v[214:217], v[68:71]
	s_setprio 0
	s_setprio 1
	v_mfma_f32_16x16x32_bf16 v[120:123], v[170:173], v[186:189], v[120:123]
	v_mfma_f32_16x16x32_bf16 v[112:115], v[178:181], v[186:189], v[112:115]
	v_mfma_f32_16x16x32_bf16 v[104:107], v[170:173], v[194:197], v[104:107]
	v_mfma_f32_16x16x32_bf16 v[96:99], v[178:181], v[194:197], v[96:99]
	v_mfma_f32_16x16x32_bf16 v[88:91], v[170:173], v[202:205], v[88:91]
	v_mfma_f32_16x16x32_bf16 v[80:83], v[178:181], v[202:205], v[80:83]
	v_mfma_f32_16x16x32_bf16 v[72:75], v[170:173], v[210:213], v[72:75]
	v_mfma_f32_16x16x32_bf16 v[64:67], v[178:181], v[210:213], v[64:67]
	v_mfma_f32_16x16x32_bf16 v[120:123], v[174:177], v[190:193], v[120:123]
	v_mfma_f32_16x16x32_bf16 v[112:115], v[182:185], v[190:193], v[112:115]
	v_mfma_f32_16x16x32_bf16 v[104:107], v[174:177], v[198:201], v[104:107]
	v_mfma_f32_16x16x32_bf16 v[96:99], v[182:185], v[198:201], v[96:99]
	v_mfma_f32_16x16x32_bf16 v[88:91], v[174:177], v[206:209], v[88:91]
	v_mfma_f32_16x16x32_bf16 v[80:83], v[182:185], v[206:209], v[80:83]
	v_mfma_f32_16x16x32_bf16 v[72:75], v[174:177], v[214:217], v[72:75]
	v_mfma_f32_16x16x32_bf16 v[64:67], v[182:185], v[214:217], v[64:67]
	s_barrier
	s_setprio 0
	s_add_i32 s50, s38, s26
	v_lshl_add_u64 v[218:219], s[22:23], 0, v[132:133]
	s_mov_b32 m0, s50
	ds_read_b128 v[186:189], v150 offset:16384
	ds_read_b128 v[190:193], v150 offset:17408
	global_load_lds_dwordx4 v[218:219], off
	s_add_i32 m0, s50, 0x2000
	s_add_u32 s50, s22, 0x40000
	v_lshl_add_u64 v[220:221], s[22:23], 0, v[128:129]
	s_addc_u32 s51, s23, 0
	s_add_i32 s52, s39, s26
	ds_read_b128 v[194:197], v150 offset:18432
	ds_read_b128 v[198:201], v150 offset:19456
	global_load_lds_dwordx4 v[220:221], off
	v_lshl_add_u64 v[222:223], s[50:51], 0, v[132:133]
	s_mov_b32 m0, s52
	v_lshl_add_u64 v[224:225], s[24:25], 0, v[130:131]
	ds_read_b128 v[202:205], v150 offset:20480
	global_load_lds_dwordx4 v[222:223], off
	v_lshl_add_u64 v[222:223], s[50:51], 0, v[128:129]
	s_add_i32 m0, s52, 0x2000
	ds_read_b128 v[206:209], v150 offset:21504
	global_load_lds_dwordx4 v[222:223], off
	v_lshl_add_u64 v[222:223], s[24:25], 0, v[134:135]
	s_mov_b32 m0, s19
	ds_read_b128 v[210:213], v150 offset:22528
	global_load_lds_dwordx4 v[222:223], off
	s_mov_b32 m0, s33
	ds_read_b128 v[214:217], v150 offset:23552
	global_load_lds_dwordx4 v[224:225], off
	s_cmp_lg_u32 s79, 1
	s_cbranch_scc1 .Ltr1613_1_w
	s_cmp_eq_u32 s70, 0
	s_cbranch_scc1 .Ltr1613_1_w
	s_cmp_eq_u32 s70, 1
	s_cbranch_scc1 .Ltr1613_1_s1
	s_cmp_eq_u32 s70, 2
	s_cbranch_scc1 .Ltr1613_1_s2
	s_cmp_eq_u32 s70, 3
	s_cbranch_scc1 .Ltr1613_1_s3
	s_cmp_eq_u32 s70, 4
	s_cbranch_scc1 .Ltr1613_1_s4
	s_cmp_eq_u32 s70, 5
	s_cbranch_scc1 .Ltr1613_1_s5
	v_add_u32_e32 v255, 0xf2000, v254
	global_store_dwordx4 v255, v[250:253], s[64:65]
	s_branch .Ltr1613_1_d

.Lpk1613_seg3:
	s_add_i32 s50, 0, 0x18000
	v_add_u32_e32 v151, s50, v145
	s_add_i32 s51, 0, 0x1c000
	ds_read_b128 v[154:157], v151
	ds_read_b128 v[158:161], v151 offset:1024
	ds_read_b128 v[162:165], v151 offset:2048
	ds_read_b128 v[166:169], v151 offset:3072
	v_add_u32_e32 v151, s51, v145
	ds_read_b128 v[170:173], v151
	ds_read_b128 v[174:177], v151 offset:1024
	ds_read_b128 v[178:181], v151 offset:2048
	ds_read_b128 v[182:185], v151 offset:3072
	s_add_u32 s24, s24, 0x40000
	s_addc_u32 s25, s25, 0
	s_mov_b32 m0, s34
	v_lshl_add_u64 v[226:227], s[24:25], 0, v[134:135]
	ds_read_b128 v[186:189], v150 offset:32768
	ds_read_b128 v[190:193], v150 offset:33792
	ds_read_b128 v[194:197], v150 offset:34816
	ds_read_b128 v[198:201], v150 offset:35840
	ds_read_b128 v[202:205], v150 offset:36864
	ds_read_b128 v[206:209], v150 offset:37888
	ds_read_b128 v[210:213], v150 offset:38912
	ds_read_b128 v[214:217], v150 offset:39936
	global_load_lds_dwordx4 v[226:227], off
	v_lshl_add_u64 v[226:227], s[24:25], 0, v[130:131]
	s_mov_b32 m0, s35
	s_nop 0
	global_load_lds_dwordx4 v[226:227], off
	s_cmp_lg_u32 s79, 2
	s_cbranch_scc1 .Ltr1613_2_w
	s_cmp_eq_u32 s70, 0
	s_cbranch_scc1 .Ltr1613_2_w
	s_cmp_eq_u32 s70, 1
	s_cbranch_scc1 .Ltr1613_2_s1
	s_cmp_eq_u32 s70, 2
	s_cbranch_scc1 .Ltr1613_2_s2
	s_cmp_eq_u32 s70, 3
	s_cbranch_scc1 .Ltr1613_2_s3
	s_cmp_eq_u32 s70, 4
	s_cbranch_scc1 .Ltr1613_2_s4
	s_cmp_eq_u32 s70, 5
	s_cbranch_scc1 .Ltr1613_2_s5
	v_add_u32_e32 v255, 0xf2000, v254
	global_store_dwordx4 v255, v[250:253], s[64:65]
	s_branch .Ltr1613_2_d

.Ltr1613_2_j:
	s_waitcnt lgkmcnt(0)
	s_setprio 1
	s_barrier
	v_mfma_f32_16x16x32_bf16 v[124:127], v[154:157], v[186:189], v[124:127]
	v_mfma_f32_16x16x32_bf16 v[116:119], v[162:165], v[186:189], v[116:119]
	v_mfma_f32_16x16x32_bf16 v[108:111], v[154:157], v[194:197], v[108:111]
	v_mfma_f32_16x16x32_bf16 v[100:103], v[162:165], v[194:197], v[100:103]
	v_mfma_f32_16x16x32_bf16 v[92:95], v[154:157], v[202:205], v[92:95]
	v_mfma_f32_16x16x32_bf16 v[84:87], v[162:165], v[202:205], v[84:87]
	v_mfma_f32_16x16x32_bf16 v[76:79], v[154:157], v[210:213], v[76:79]
	v_mfma_f32_16x16x32_bf16 v[68:71], v[162:165], v[210:213], v[68:71]
	v_mfma_f32_16x16x32_bf16 v[124:127], v[158:161], v[190:193], v[124:127]
	v_mfma_f32_16x16x32_bf16 v[116:119], v[166:169], v[190:193], v[116:119]
	v_mfma_f32_16x16x32_bf16 v[108:111], v[158:161], v[198:201], v[108:111]
	v_mfma_f32_16x16x32_bf16 v[100:103], v[166:169], v[198:201], v[100:103]
	v_mfma_f32_16x16x32_bf16 v[92:95], v[158:161], v[206:209], v[92:95]
	v_mfma_f32_16x16x32_bf16 v[84:87], v[166:169], v[206:209], v[84:87]
	v_mfma_f32_16x16x32_bf16 v[76:79], v[158:161], v[214:217], v[76:79]
	v_mfma_f32_16x16x32_bf16 v[68:71], v[166:169], v[214:217], v[68:71]
	s_setprio 0
	s_setprio 1
	v_mfma_f32_16x16x32_bf16 v[120:123], v[170:173], v[186:189], v[120:123]
	v_mfma_f32_16x16x32_bf16 v[112:115], v[178:181], v[186:189], v[112:115]
	v_mfma_f32_16x16x32_bf16 v[104:107], v[170:173], v[194:197], v[104:107]
	v_mfma_f32_16x16x32_bf16 v[96:99], v[178:181], v[194:197], v[96:99]
	v_mfma_f32_16x16x32_bf16 v[88:91], v[170:173], v[202:205], v[88:91]
	v_mfma_f32_16x16x32_bf16 v[80:83], v[178:181], v[202:205], v[80:83]
	v_mfma_f32_16x16x32_bf16 v[72:75], v[170:173], v[210:213], v[72:75]
	v_mfma_f32_16x16x32_bf16 v[64:67], v[178:181], v[210:213], v[64:67]
	v_mfma_f32_16x16x32_bf16 v[120:123], v[174:177], v[190:193], v[120:123]
	v_mfma_f32_16x16x32_bf16 v[112:115], v[182:185], v[190:193], v[112:115]
	v_mfma_f32_16x16x32_bf16 v[104:107], v[174:177], v[198:201], v[104:107]
	v_mfma_f32_16x16x32_bf16 v[96:99], v[182:185], v[198:201], v[96:99]
	v_mfma_f32_16x16x32_bf16 v[88:91], v[174:177], v[206:209], v[88:91]
	v_mfma_f32_16x16x32_bf16 v[80:83], v[182:185], v[206:209], v[80:83]
	v_mfma_f32_16x16x32_bf16 v[72:75], v[174:177], v[214:217], v[72:75]
	v_mfma_f32_16x16x32_bf16 v[64:67], v[182:185], v[214:217], v[64:67]
	s_barrier
	s_setprio 0
	s_add_i32 s24, s50, s26
	v_lshl_add_u64 v[218:219], v[218:219], 0, s[6:7]
	s_mov_b32 m0, s24
	ds_read_b128 v[186:189], v150 offset:49152
	ds_read_b128 v[190:193], v150 offset:50176
	global_load_lds_dwordx4 v[218:219], off
	s_add_i32 m0, s24, 0x2000
	s_add_u32 s22, s22, 0x40080
	v_lshl_add_u64 v[218:219], v[220:221], 0, s[6:7]
	s_addc_u32 s23, s23, 0
	s_add_i32 s24, s51, s26
	ds_read_b128 v[194:197], v150 offset:51200
	ds_read_b128 v[198:201], v150 offset:52224
	global_load_lds_dwordx4 v[218:219], off
	v_lshl_add_u64 v[218:219], s[22:23], 0, v[132:133]
	s_mov_b32 m0, s24
	ds_read_b128 v[202:205], v150 offset:53248
	global_load_lds_dwordx4 v[218:219], off
	v_lshl_add_u64 v[218:219], s[22:23], 0, v[128:129]
	s_add_i32 m0, s24, 0x2000
	ds_read_b128 v[206:209], v150 offset:54272
	global_load_lds_dwordx4 v[218:219], off
	v_lshl_add_u64 v[218:219], v[222:223], 0, s[6:7]
	s_mov_b32 m0, s36
	ds_read_b128 v[210:213], v150 offset:55296
	global_load_lds_dwordx4 v[218:219], off
	v_lshl_add_u64 v[218:219], v[224:225], 0, s[6:7]
	s_mov_b32 m0, s37
	ds_read_b128 v[214:217], v150 offset:56320
	global_load_lds_dwordx4 v[218:219], off
	s_cmp_lg_u32 s79, 3
	s_cbranch_scc1 .Ltr1613_3_w
	s_cmp_eq_u32 s70, 0
	s_cbranch_scc1 .Ltr1613_3_w
	s_cmp_eq_u32 s70, 1
	s_cbranch_scc1 .Ltr1613_3_s1
	s_cmp_eq_u32 s70, 2
	s_cbranch_scc1 .Ltr1613_3_s2
	s_cmp_eq_u32 s70, 3
	s_cbranch_scc1 .Ltr1613_3_s3
	s_cmp_eq_u32 s70, 4
	s_cbranch_scc1 .Ltr1613_3_s4
	s_cmp_eq_u32 s70, 5
	s_cbranch_scc1 .Ltr1613_3_s5
	v_add_u32_e32 v255, 0xf2000, v254
	global_store_dwordx4 v255, v[250:253], s[64:65]
	s_branch .Ltr1613_3_d

; __device__ __forceinline__ unsigned cvt_pk_bf16(float lo, float hi) { unsigned r; asm volatile("v_cvt_pk_bf16_f32 %0, %1, %2" : "=v"(r) : "v"(lo), "v"(hi)); return r; }
;     __device__ __forceinline__ void operator()(Acc& acc, const Unit& u, int wr, int wc, int fr, int fq) const {
;         const int row0 = u.pm * BM + wr * 64 + fr, col0 = u.pn * 128 + wc * 32 + 8 * fq;
; #pragma unroll
;         for (int ai = 0; ai < 2; ++ai)
; #pragma unroll
;             for (int m = 0; m < 4; ++m) {
;                 const int row = row0 + ai * HALF + m * 16;
;                 const float r = rs[u.idx * BM + wr * 64 + fr + ai * HALF + m * 16];
;                 const float c1 = -r * 1.4426950408889634f, r2 = r * r;
;                 f32x4 o[2];
; #pragma unroll
;                 for (int n = 0; n < 2; ++n) {
;                     const f32x4 g = acc[ai][0][m][n], up = acc[ai][1][m][n];
;                     const f32x4 t = g * c1; f32x4 e;
; #pragma unroll
;                     for (int i = 0; i < 4; ++i) e[i] = __builtin_amdgcn_exp2f(t[i]);
;                     const f32x4 d = e + 1.0f; f32x4 q;
; #pragma unroll
;                     for (int i = 0; i < 4; ++i) q[i] = __builtin_amdgcn_rcpf(d[i]);
;                     o[n] = (g * up) * (q * r2);
;                 }
;                 u32x4 w; w.x = cvt_pk_bf16(o[0][0], o[0][1]); w.y = cvt_pk_bf16(o[0][2], o[0][3]); w.z = cvt_pk_bf16(o[1][0], o[1][1]); w.w = cvt_pk_bf16(o[1][2], o[1][3]);
;                 *(u32x4*)(O + (size_t)row * DFF + col0) = w;
.Ltr1613_3_j:
	s_waitcnt lgkmcnt(0)
	s_setprio 1
	s_barrier
	v_mfma_f32_16x16x32_bf16 v[60:63], v[154:157], v[186:189], v[60:63]
	v_mfma_f32_16x16x32_bf16 v[52:55], v[162:165], v[186:189], v[52:55]
	v_mfma_f32_16x16x32_bf16 v[44:47], v[154:157], v[194:197], v[44:47]
	v_mfma_f32_16x16x32_bf16 v[36:39], v[162:165], v[194:197], v[36:39]
	v_mfma_f32_16x16x32_bf16 v[28:31], v[154:157], v[202:205], v[28:31]
	v_mfma_f32_16x16x32_bf16 v[20:23], v[162:165], v[202:205], v[20:23]
	v_mfma_f32_16x16x32_bf16 v[12:15], v[154:157], v[210:213], v[12:15]
	v_mfma_f32_16x16x32_bf16 v[4:7], v[162:165], v[210:213], v[4:7]
	v_mfma_f32_16x16x32_bf16 v[60:63], v[158:161], v[190:193], v[60:63]
	v_mfma_f32_16x16x32_bf16 v[52:55], v[166:169], v[190:193], v[52:55]
	v_mfma_f32_16x16x32_bf16 v[44:47], v[158:161], v[198:201], v[44:47]
	v_mfma_f32_16x16x32_bf16 v[36:39], v[166:169], v[198:201], v[36:39]
	v_mfma_f32_16x16x32_bf16 v[28:31], v[158:161], v[206:209], v[28:31]
	v_mfma_f32_16x16x32_bf16 v[20:23], v[166:169], v[206:209], v[20:23]
	v_mfma_f32_16x16x32_bf16 v[12:15], v[158:161], v[214:217], v[12:15]
	v_mfma_f32_16x16x32_bf16 v[4:7], v[166:169], v[214:217], v[4:7]
	s_setprio 0
	s_setprio 1
	v_mfma_f32_16x16x32_bf16 v[56:59], v[170:173], v[186:189], v[56:59]
	v_mfma_f32_16x16x32_bf16 v[48:51], v[178:181], v[186:189], v[48:51]
	v_mfma_f32_16x16x32_bf16 v[40:43], v[170:173], v[194:197], v[40:43]
	v_mfma_f32_16x16x32_bf16 v[32:35], v[178:181], v[194:197], v[32:35]
	v_mfma_f32_16x16x32_bf16 v[24:27], v[170:173], v[202:205], v[24:27]
	v_mfma_f32_16x16x32_bf16 v[16:19], v[178:181], v[202:205], v[16:19]
	v_mfma_f32_16x16x32_bf16 v[8:11], v[170:173], v[210:213], v[8:11]
	v_mfma_f32_16x16x32_bf16 v[0:3], v[178:181], v[210:213], v[0:3]
	v_mfma_f32_16x16x32_bf16 v[56:59], v[174:177], v[190:193], v[56:59]
	v_mfma_f32_16x16x32_bf16 v[48:51], v[182:185], v[190:193], v[48:51]
	v_mfma_f32_16x16x32_bf16 v[40:43], v[174:177], v[198:201], v[40:43]
	v_mfma_f32_16x16x32_bf16 v[32:35], v[182:185], v[198:201], v[32:35]
	v_mfma_f32_16x16x32_bf16 v[24:27], v[174:177], v[206:209], v[24:27]
	v_mfma_f32_16x16x32_bf16 v[16:19], v[182:185], v[206:209], v[16:19]
	v_mfma_f32_16x16x32_bf16 v[8:11], v[174:177], v[214:217], v[8:11]
	v_mfma_f32_16x16x32_bf16 v[0:3], v[182:185], v[214:217], v[0:3]
	s_barrier
	s_setprio 0
	s_add_i32 s49, s49, 2
	s_add_u32 s20, s20, 0x100
	s_addc_u32 s21, s21, 0
	s_add_u32 s47, s47, 0x100
	s_addc_u32 s48, s48, 0
	s_cmp_gt_u32 s49, 13
	s_cbranch_scc0 .LBB0_1613
	s_and_b64 vcc, exec, s[8:9]
	s_cbranch_vccz .LBB0_1616
	s_barrier
.LBB0_1616:
	v_lshl_add_u32 v154, s43, 10, v146
	ds_read_b32 v200, v154
	ds_read_b32 v201, v154 offset:64
	ds_read_b32 v202, v154 offset:128
	ds_read_b32 v203, v154 offset:192
	ds_read_b32 v204, v154 offset:512
	ds_read_b32 v205, v154 offset:576
	ds_read_b32 v206, v154 offset:640
	ds_read_b32 v207, v154 offset:704
	v_lshl_or_b32 v156, s44, 7, v147
	v_lshl_add_u32 v151, s18, 8, v144
	v_lshlrev_b32_e32 v156, 1, v156
	v_mov_b32_e32 v198, 1.0
	v_mad_u32_u24 v155, v151, s40, v156
	s_waitcnt lgkmcnt(0)
	v_mul_f32_e32 v158, 0xbfb8aa3b, v200
	v_mul_f32_e32 v160, v200, v200
	v_pk_mul_f32 v[162:163], v[124:125], v[158:159] op_sel_hi:[1,0]
	v_pk_mul_f32 v[164:165], v[126:127], v[158:159] op_sel_hi:[1,0]
	v_pk_mul_f32 v[166:167], v[116:117], v[158:159] op_sel_hi:[1,0]
	v_pk_mul_f32 v[168:169], v[118:119], v[158:159] op_sel_hi:[1,0]
	v_exp_f32_e32 v162, v162
	v_exp_f32_e32 v163, v163
	v_pk_mul_f32 v[120:121], v[124:125], v[120:121]
	v_exp_f32_e32 v164, v164
	v_exp_f32_e32 v165, v165
	v_pk_mul_f32 v[122:123], v[126:127], v[122:123]
	v_exp_f32_e32 v166, v166
	v_exp_f32_e32 v167, v167
	v_pk_mul_f32 v[112:113], v[116:117], v[112:113]
	v_exp_f32_e32 v168, v168
	v_exp_f32_e32 v169, v169
	v_pk_mul_f32 v[114:115], v[118:119], v[114:115]
	v_pk_add_f32 v[162:163], v[162:163], v[198:199] op_sel_hi:[1,0]
	v_pk_add_f32 v[164:165], v[164:165], v[198:199] op_sel_hi:[1,0]
	v_pk_add_f32 v[166:167], v[166:167], v[198:199] op_sel_hi:[1,0]
	v_pk_add_f32 v[168:169], v[168:169], v[198:199] op_sel_hi:[1,0]
	v_rcp_f32_e32 v162, v162
	v_rcp_f32_e32 v163, v163
	v_rcp_f32_e32 v164, v164
	v_rcp_f32_e32 v165, v165
	v_rcp_f32_e32 v166, v166
	v_rcp_f32_e32 v167, v167
	v_rcp_f32_e32 v168, v168
	v_rcp_f32_e32 v169, v169
	v_pk_mul_f32 v[162:163], v[160:161], v[162:163] op_sel_hi:[0,1]
	v_pk_mul_f32 v[164:165], v[160:161], v[164:165] op_sel_hi:[0,1]
	v_pk_mul_f32 v[166:167], v[160:161], v[166:167] op_sel_hi:[0,1]
	v_pk_mul_f32 v[168:169], v[160:161], v[168:169] op_sel_hi:[0,1]
	v_pk_mul_f32 v[120:121], v[120:121], v[162:163]
	v_pk_mul_f32 v[122:123], v[122:123], v[164:165]
	v_pk_mul_f32 v[112:113], v[112:113], v[166:167]
	v_pk_mul_f32 v[114:115], v[114:115], v[168:169]
	v_cvt_pk_bf16_f32 v170, v120, v121
	v_cvt_pk_bf16_f32 v171, v122, v123
	v_cvt_pk_bf16_f32 v172, v112, v113
	v_cvt_pk_bf16_f32 v173, v114, v115
	global_store_dwordx4 v155, v[170:173], s[64:65]
	v_mul_f32_e32 v158, 0xbfb8aa3b, v201
	v_mul_f32_e32 v160, v201, v201
	v_pk_mul_f32 v[162:163], v[108:109], v[158:159] op_sel_hi:[1,0]
	v_pk_mul_f32 v[164:165], v[110:111], v[158:159] op_sel_hi:[1,0]
	v_pk_mul_f32 v[166:167], v[100:101], v[158:159] op_sel_hi:[1,0]
	v_pk_mul_f32 v[168:169], v[102:103], v[158:159] op_sel_hi:[1,0]
	v_exp_f32_e32 v162, v162
	v_exp_f32_e32 v163, v163
	v_pk_mul_f32 v[104:105], v[108:109], v[104:105]
	v_exp_f32_e32 v164, v164
	v_exp_f32_e32 v165, v165
	v_pk_mul_f32 v[106:107], v[110:111], v[106:107]
	v_exp_f32_e32 v166, v166
	v_exp_f32_e32 v167, v167
	v_pk_mul_f32 v[96:97], v[100:101], v[96:97]
	v_exp_f32_e32 v168, v168
	v_exp_f32_e32 v169, v169
	v_pk_mul_f32 v[98:99], v[102:103], v[98:99]
; __device__ __forceinline__ unsigned cvt_pk_bf16(float lo, float hi) { unsigned r; asm volatile("v_cvt_pk_bf16_f32 %0, %1, %2" : "=v"(r) : "v"(lo), "v"(hi)); return r; }
;     __device__ __forceinline__ void operator()(Acc& acc, const Unit& u, int wr, int wc, int fr, int fq) const {
;     ...
;             for (int m = 0; m < 4; ++m) {
;                 const int row = row0 + ai * HALF + m * 16;
;                 const float r = rs[u.idx * BM + wr * 64 + fr + ai * HALF + m * 16];
;                 const float c1 = -r * 1.4426950408889634f, r2 = r * r;
;                 f32x4 o[2];
; #pragma unroll
;                 for (int n = 0; n < 2; ++n) {
;                     const f32x4 g = acc[ai][0][m][n], up = acc[ai][1][m][n];
;                     const f32x4 t = g * c1; f32x4 e;
; #pragma unroll
;                     for (int i = 0; i < 4; ++i) e[i] = __builtin_amdgcn_exp2f(t[i]);
;                     const f32x4 d = e + 1.0f; f32x4 q;
; #pragma unroll
;                     for (int i = 0; i < 4; ++i) q[i] = __builtin_amdgcn_rcpf(d[i]);
;                     o[n] = (g * up) * (q * r2);
;                 }
;                 u32x4 w; w.x = cvt_pk_bf16(o[0][0], o[0][1]); w.y = cvt_pk_bf16(o[0][2], o[0][3]); w.z = cvt_pk_bf16(o[1][0], o[1][1]); w.w = cvt_pk_bf16(o[1][2], o[1][3]);
;                 *(u32x4*)(O + (size_t)row * DFF + col0) = w;
	v_pk_add_f32 v[162:163], v[162:163], v[198:199] op_sel_hi:[1,0]
	v_pk_add_f32 v[164:165], v[164:165], v[198:199] op_sel_hi:[1,0]
	v_pk_add_f32 v[166:167], v[166:167], v[198:199] op_sel_hi:[1,0]
	v_pk_add_f32 v[168:169], v[168:169], v[198:199] op_sel_hi:[1,0]
	v_rcp_f32_e32 v162, v162
	v_rcp_f32_e32 v163, v163
	v_rcp_f32_e32 v164, v164
	v_rcp_f32_e32 v165, v165
	v_rcp_f32_e32 v166, v166
	v_rcp_f32_e32 v167, v167
	v_rcp_f32_e32 v168, v168
	v_rcp_f32_e32 v169, v169
	v_pk_mul_f32 v[162:163], v[160:161], v[162:163] op_sel_hi:[0,1]
	v_pk_mul_f32 v[164:165], v[160:161], v[164:165] op_sel_hi:[0,1]
	v_pk_mul_f32 v[166:167], v[160:161], v[166:167] op_sel_hi:[0,1]
	v_pk_mul_f32 v[168:169], v[160:161], v[168:169] op_sel_hi:[0,1]
	v_pk_mul_f32 v[104:105], v[104:105], v[162:163]
	v_pk_mul_f32 v[106:107], v[106:107], v[164:165]
	v_pk_mul_f32 v[96:97], v[96:97], v[166:167]
	v_pk_mul_f32 v[98:99], v[98:99], v[168:169]
	v_cvt_pk_bf16_f32 v176, v104, v105
	v_cvt_pk_bf16_f32 v177, v106, v107
	v_cvt_pk_bf16_f32 v178, v96, v97
	v_cvt_pk_bf16_f32 v179, v98, v99
	v_add_u32_e32 v175, 0x16000, v155
	global_store_dwordx4 v175, v[176:179], s[64:65]
	v_mul_f32_e32 v158, 0xbfb8aa3b, v202
	v_mul_f32_e32 v160, v202, v202
	v_pk_mul_f32 v[162:163], v[92:93], v[158:159] op_sel_hi:[1,0]
	v_pk_mul_f32 v[164:165], v[94:95], v[158:159] op_sel_hi:[1,0]
	v_pk_mul_f32 v[166:167], v[84:85], v[158:159] op_sel_hi:[1,0]
	v_pk_mul_f32 v[168:169], v[86:87], v[158:159] op_sel_hi:[1,0]
	v_exp_f32_e32 v162, v162
	v_exp_f32_e32 v163, v163
	v_pk_mul_f32 v[88:89], v[92:93], v[88:89]
	v_exp_f32_e32 v164, v164
	v_exp_f32_e32 v165, v165
	v_pk_mul_f32 v[90:91], v[94:95], v[90:91]
	v_exp_f32_e32 v166, v166
	v_exp_f32_e32 v167, v167
	v_pk_mul_f32 v[80:81], v[84:85], v[80:81]
	v_exp_f32_e32 v168, v168
	v_exp_f32_e32 v169, v169
	v_pk_mul_f32 v[82:83], v[86:87], v[82:83]
	v_pk_add_f32 v[162:163], v[162:163], v[198:199] op_sel_hi:[1,0]
	v_pk_add_f32 v[164:165], v[164:165], v[198:199] op_sel_hi:[1,0]
	v_pk_add_f32 v[166:167], v[166:167], v[198:199] op_sel_hi:[1,0]
	v_pk_add_f32 v[168:169], v[168:169], v[198:199] op_sel_hi:[1,0]
	v_rcp_f32_e32 v162, v162
	v_rcp_f32_e32 v163, v163
	v_rcp_f32_e32 v164, v164
	v_rcp_f32_e32 v165, v165
	v_rcp_f32_e32 v166, v166
	v_rcp_f32_e32 v167, v167
	v_rcp_f32_e32 v168, v168
	v_rcp_f32_e32 v169, v169
	v_pk_mul_f32 v[162:163], v[160:161], v[162:163] op_sel_hi:[0,1]
	v_pk_mul_f32 v[164:165], v[160:161], v[164:165] op_sel_hi:[0,1]
	v_pk_mul_f32 v[166:167], v[160:161], v[166:167] op_sel_hi:[0,1]
	v_pk_mul_f32 v[168:169], v[160:161], v[168:169] op_sel_hi:[0,1]
	v_pk_mul_f32 v[88:89], v[88:89], v[162:163]
	v_pk_mul_f32 v[90:91], v[90:91], v[164:165]
	v_pk_mul_f32 v[80:81], v[80:81], v[166:167]
	v_pk_mul_f32 v[82:83], v[82:83], v[168:169]
	v_cvt_pk_bf16_f32 v228, v88, v89
	v_cvt_pk_bf16_f32 v229, v90, v91
	v_cvt_pk_bf16_f32 v230, v80, v81
	v_cvt_pk_bf16_f32 v231, v82, v83
	v_mul_f32_e32 v158, 0xbfb8aa3b, v203
	v_mul_f32_e32 v160, v203, v203
	v_pk_mul_f32 v[162:163], v[76:77], v[158:159] op_sel_hi:[1,0]
	v_pk_mul_f32 v[164:165], v[78:79], v[158:159] op_sel_hi:[1,0]
	v_pk_mul_f32 v[166:167], v[68:69], v[158:159] op_sel_hi:[1,0]
	v_pk_mul_f32 v[168:169], v[70:71], v[158:159] op_sel_hi:[1,0]
	v_exp_f32_e32 v162, v162
	v_exp_f32_e32 v163, v163
	v_pk_mul_f32 v[72:73], v[76:77], v[72:73]
	v_exp_f32_e32 v164, v164
	v_exp_f32_e32 v165, v165
	v_pk_mul_f32 v[74:75], v[78:79], v[74:75]
	v_exp_f32_e32 v166, v166
	v_exp_f32_e32 v167, v167
	v_pk_mul_f32 v[64:65], v[68:69], v[64:65]
	v_exp_f32_e32 v168, v168
	v_exp_f32_e32 v169, v169
	v_pk_mul_f32 v[66:67], v[70:71], v[66:67]
	v_pk_add_f32 v[162:163], v[162:163], v[198:199] op_sel_hi:[1,0]
	v_pk_add_f32 v[164:165], v[164:165], v[198:199] op_sel_hi:[1,0]
	v_pk_add_f32 v[166:167], v[166:167], v[198:199] op_sel_hi:[1,0]
	v_pk_add_f32 v[168:169], v[168:169], v[198:199] op_sel_hi:[1,0]
	v_rcp_f32_e32 v162, v162
	v_rcp_f32_e32 v163, v163
	v_rcp_f32_e32 v164, v164
	v_rcp_f32_e32 v165, v165
	v_rcp_f32_e32 v166, v166
	v_rcp_f32_e32 v167, v167
	v_rcp_f32_e32 v168, v168
	v_rcp_f32_e32 v169, v169
	v_pk_mul_f32 v[162:163], v[160:161], v[162:163] op_sel_hi:[0,1]
	v_pk_mul_f32 v[164:165], v[160:161], v[164:165] op_sel_hi:[0,1]
	v_pk_mul_f32 v[166:167], v[160:161], v[166:167] op_sel_hi:[0,1]
	v_pk_mul_f32 v[168:169], v[160:161], v[168:169] op_sel_hi:[0,1]
	v_pk_mul_f32 v[72:73], v[72:73], v[162:163]
	v_pk_mul_f32 v[74:75], v[74:75], v[164:165]
	v_pk_mul_f32 v[64:65], v[64:65], v[166:167]
	v_pk_mul_f32 v[66:67], v[66:67], v[168:169]
	v_cvt_pk_bf16_f32 v232, v72, v73
	v_cvt_pk_bf16_f32 v233, v74, v75
	v_cvt_pk_bf16_f32 v234, v64, v65
	v_cvt_pk_bf16_f32 v235, v66, v67
	v_mul_f32_e32 v158, 0xbfb8aa3b, v204
	v_mul_f32_e32 v160, v204, v204
	v_pk_mul_f32 v[162:163], v[60:61], v[158:159] op_sel_hi:[1,0]
	v_pk_mul_f32 v[164:165], v[62:63], v[158:159] op_sel_hi:[1,0]
	v_pk_mul_f32 v[166:167], v[52:53], v[158:159] op_sel_hi:[1,0]
	v_pk_mul_f32 v[168:169], v[54:55], v[158:159] op_sel_hi:[1,0]
	v_exp_f32_e32 v162, v162
	v_exp_f32_e32 v163, v163
	v_pk_mul_f32 v[56:57], v[60:61], v[56:57]
	v_exp_f32_e32 v164, v164
	v_exp_f32_e32 v165, v165
	v_pk_mul_f32 v[58:59], v[62:63], v[58:59]
	v_exp_f32_e32 v166, v166
	v_exp_f32_e32 v167, v167
	v_pk_mul_f32 v[48:49], v[52:53], v[48:49]
	v_exp_f32_e32 v168, v168
	v_exp_f32_e32 v169, v169
	v_pk_mul_f32 v[50:51], v[54:55], v[50:51]
	v_pk_add_f32 v[162:163], v[162:163], v[198:199] op_sel_hi:[1,0]
	v_pk_add_f32 v[164:165], v[164:165], v[198:199] op_sel_hi:[1,0]
	v_pk_add_f32 v[166:167], v[166:167], v[198:199] op_sel_hi:[1,0]
	v_pk_add_f32 v[168:169], v[168:169], v[198:199] op_sel_hi:[1,0]
	v_rcp_f32_e32 v162, v162
	v_rcp_f32_e32 v163, v163
; __device__ __forceinline__ unsigned cvt_pk_bf16(float lo, float hi) { unsigned r; asm volatile("v_cvt_pk_bf16_f32 %0, %1, %2" : "=v"(r) : "v"(lo), "v"(hi)); return r; }
; #define PG8_BAR __builtin_amdgcn_s_barrier()
;     __device__ __forceinline__ void operator()(Acc& acc, const Unit& u, int wr, int wc, int fr, int fq) const {
;     ...
;             for (int m = 0; m < 4; ++m) {
;                 const int row = row0 + ai * HALF + m * 16;
;                 const float r = rs[u.idx * BM + wr * 64 + fr + ai * HALF + m * 16];
;                 const float c1 = -r * 1.4426950408889634f, r2 = r * r;
;                 f32x4 o[2];
; #pragma unroll
;                 for (int n = 0; n < 2; ++n) {
;                     const f32x4 g = acc[ai][0][m][n], up = acc[ai][1][m][n];
;                     const f32x4 t = g * c1; f32x4 e;
; #pragma unroll
;                     for (int i = 0; i < 4; ++i) e[i] = __builtin_amdgcn_exp2f(t[i]);
;                     const f32x4 d = e + 1.0f; f32x4 q;
; #pragma unroll
;                     for (int i = 0; i < 4; ++i) q[i] = __builtin_amdgcn_rcpf(d[i]);
;                     o[n] = (g * up) * (q * r2);
;                 }
;                 u32x4 w; w.x = cvt_pk_bf16(o[0][0], o[0][1]); w.y = cvt_pk_bf16(o[0][2], o[0][3]); w.z = cvt_pk_bf16(o[1][0], o[1][1]); w.w = cvt_pk_bf16(o[1][2], o[1][3]);
;                 *(u32x4*)(O + (size_t)row * DFF + col0) = w;
; template <class Epi, class Sched, bool ALIGN_EPI>
; __device__ __forceinline__ void gemm_phase(LAS unsigned char* lds, const Gemm g, const Sched& S, const Epi& E) {
;     ...
;         if (!has_next) break;
; #pragma unroll
;         for (int a = 0; a < 2; ++a)
; #pragma unroll
;             for (int b = 0; b < 2; ++b)
; #pragma unroll
;                 for (int m = 0; m < 4; ++m)
; #pragma unroll
;                     for (int n = 0; n < 2; ++n) acc[a][b][m][n] = (f32x4){0.f, 0.f, 0.f, 0.f};
;         cur = nxt; cA = nA; cB = nB; ++ui;
;         if constexpr (ALIGN_EPI) { if (wr == 1) PG8_BAR; }
	v_rcp_f32_e32 v164, v164
	v_rcp_f32_e32 v165, v165
	v_rcp_f32_e32 v166, v166
	v_rcp_f32_e32 v167, v167
	v_rcp_f32_e32 v168, v168
	v_rcp_f32_e32 v169, v169
	v_pk_mul_f32 v[162:163], v[160:161], v[162:163] op_sel_hi:[0,1]
	v_pk_mul_f32 v[164:165], v[160:161], v[164:165] op_sel_hi:[0,1]
	v_pk_mul_f32 v[166:167], v[160:161], v[166:167] op_sel_hi:[0,1]
	v_pk_mul_f32 v[168:169], v[160:161], v[168:169] op_sel_hi:[0,1]
	v_pk_mul_f32 v[56:57], v[56:57], v[162:163]
	v_pk_mul_f32 v[58:59], v[58:59], v[164:165]
	v_pk_mul_f32 v[48:49], v[48:49], v[166:167]
	v_pk_mul_f32 v[50:51], v[50:51], v[168:169]
	v_cvt_pk_bf16_f32 v236, v56, v57
	v_cvt_pk_bf16_f32 v237, v58, v59
	v_cvt_pk_bf16_f32 v238, v48, v49
	v_cvt_pk_bf16_f32 v239, v50, v51
	v_mul_f32_e32 v158, 0xbfb8aa3b, v205
	v_mul_f32_e32 v160, v205, v205
	v_pk_mul_f32 v[162:163], v[44:45], v[158:159] op_sel_hi:[1,0]
	v_pk_mul_f32 v[164:165], v[46:47], v[158:159] op_sel_hi:[1,0]
	v_pk_mul_f32 v[166:167], v[36:37], v[158:159] op_sel_hi:[1,0]
	v_pk_mul_f32 v[168:169], v[38:39], v[158:159] op_sel_hi:[1,0]
	v_exp_f32_e32 v162, v162
	v_exp_f32_e32 v163, v163
	v_pk_mul_f32 v[40:41], v[44:45], v[40:41]
	v_exp_f32_e32 v164, v164
	v_exp_f32_e32 v165, v165
	v_pk_mul_f32 v[42:43], v[46:47], v[42:43]
	v_exp_f32_e32 v166, v166
	v_exp_f32_e32 v167, v167
	v_pk_mul_f32 v[32:33], v[36:37], v[32:33]
	v_exp_f32_e32 v168, v168
	v_exp_f32_e32 v169, v169
	v_pk_mul_f32 v[34:35], v[38:39], v[34:35]
	v_pk_add_f32 v[162:163], v[162:163], v[198:199] op_sel_hi:[1,0]
	v_pk_add_f32 v[164:165], v[164:165], v[198:199] op_sel_hi:[1,0]
	v_pk_add_f32 v[166:167], v[166:167], v[198:199] op_sel_hi:[1,0]
	v_pk_add_f32 v[168:169], v[168:169], v[198:199] op_sel_hi:[1,0]
	v_rcp_f32_e32 v162, v162
	v_rcp_f32_e32 v163, v163
	v_rcp_f32_e32 v164, v164
	v_rcp_f32_e32 v165, v165
	v_rcp_f32_e32 v166, v166
	v_rcp_f32_e32 v167, v167
	v_rcp_f32_e32 v168, v168
	v_rcp_f32_e32 v169, v169
	v_pk_mul_f32 v[162:163], v[160:161], v[162:163] op_sel_hi:[0,1]
	v_pk_mul_f32 v[164:165], v[160:161], v[164:165] op_sel_hi:[0,1]
	v_pk_mul_f32 v[166:167], v[160:161], v[166:167] op_sel_hi:[0,1]
	v_pk_mul_f32 v[168:169], v[160:161], v[168:169] op_sel_hi:[0,1]
	v_pk_mul_f32 v[40:41], v[40:41], v[162:163]
	v_pk_mul_f32 v[42:43], v[42:43], v[164:165]
	v_pk_mul_f32 v[32:33], v[32:33], v[166:167]
	v_pk_mul_f32 v[34:35], v[34:35], v[168:169]
	v_cvt_pk_bf16_f32 v240, v40, v41
	v_cvt_pk_bf16_f32 v241, v42, v43
	v_cvt_pk_bf16_f32 v242, v32, v33
	v_cvt_pk_bf16_f32 v243, v34, v35
	v_mul_f32_e32 v158, 0xbfb8aa3b, v206
	v_mul_f32_e32 v160, v206, v206
	v_pk_mul_f32 v[162:163], v[28:29], v[158:159] op_sel_hi:[1,0]
	v_pk_mul_f32 v[164:165], v[30:31], v[158:159] op_sel_hi:[1,0]
	v_pk_mul_f32 v[166:167], v[20:21], v[158:159] op_sel_hi:[1,0]
	v_pk_mul_f32 v[168:169], v[22:23], v[158:159] op_sel_hi:[1,0]
	v_exp_f32_e32 v162, v162
	v_exp_f32_e32 v163, v163
	v_pk_mul_f32 v[24:25], v[28:29], v[24:25]
	v_exp_f32_e32 v164, v164
	v_exp_f32_e32 v165, v165
	v_pk_mul_f32 v[26:27], v[30:31], v[26:27]
	v_exp_f32_e32 v166, v166
	v_exp_f32_e32 v167, v167
	v_pk_mul_f32 v[16:17], v[20:21], v[16:17]
	v_exp_f32_e32 v168, v168
	v_exp_f32_e32 v169, v169
	v_pk_mul_f32 v[18:19], v[22:23], v[18:19]
	v_pk_add_f32 v[162:163], v[162:163], v[198:199] op_sel_hi:[1,0]
	v_pk_add_f32 v[164:165], v[164:165], v[198:199] op_sel_hi:[1,0]
	v_pk_add_f32 v[166:167], v[166:167], v[198:199] op_sel_hi:[1,0]
	v_pk_add_f32 v[168:169], v[168:169], v[198:199] op_sel_hi:[1,0]
	v_rcp_f32_e32 v162, v162
	v_rcp_f32_e32 v163, v163
	v_rcp_f32_e32 v164, v164
	v_rcp_f32_e32 v165, v165
	v_rcp_f32_e32 v166, v166
	v_rcp_f32_e32 v167, v167
	v_rcp_f32_e32 v168, v168
	v_rcp_f32_e32 v169, v169
	v_pk_mul_f32 v[162:163], v[160:161], v[162:163] op_sel_hi:[0,1]
	v_pk_mul_f32 v[164:165], v[160:161], v[164:165] op_sel_hi:[0,1]
	v_pk_mul_f32 v[166:167], v[160:161], v[166:167] op_sel_hi:[0,1]
	v_pk_mul_f32 v[168:169], v[160:161], v[168:169] op_sel_hi:[0,1]
	v_pk_mul_f32 v[24:25], v[24:25], v[162:163]
	v_pk_mul_f32 v[26:27], v[26:27], v[164:165]
	v_pk_mul_f32 v[16:17], v[16:17], v[166:167]
	v_pk_mul_f32 v[18:19], v[18:19], v[168:169]
	v_cvt_pk_bf16_f32 v246, v24, v25
	v_cvt_pk_bf16_f32 v247, v26, v27
	v_cvt_pk_bf16_f32 v248, v16, v17
	v_cvt_pk_bf16_f32 v249, v18, v19
	v_mul_f32_e32 v158, 0xbfb8aa3b, v207
	v_mul_f32_e32 v160, v207, v207
	v_pk_mul_f32 v[162:163], v[12:13], v[158:159] op_sel_hi:[1,0]
	v_pk_mul_f32 v[164:165], v[14:15], v[158:159] op_sel_hi:[1,0]
	v_pk_mul_f32 v[166:167], v[4:5], v[158:159] op_sel_hi:[1,0]
	v_pk_mul_f32 v[168:169], v[6:7], v[158:159] op_sel_hi:[1,0]
	v_exp_f32_e32 v162, v162
	v_exp_f32_e32 v163, v163
	v_pk_mul_f32 v[8:9], v[12:13], v[8:9]
	v_exp_f32_e32 v164, v164
	v_exp_f32_e32 v165, v165
	v_pk_mul_f32 v[10:11], v[14:15], v[10:11]
	v_exp_f32_e32 v166, v166
	v_exp_f32_e32 v167, v167
	v_pk_mul_f32 v[0:1], v[4:5], v[0:1]
	v_exp_f32_e32 v168, v168
	v_exp_f32_e32 v169, v169
	v_pk_mul_f32 v[2:3], v[6:7], v[2:3]
	v_pk_add_f32 v[162:163], v[162:163], v[198:199] op_sel_hi:[1,0]
	v_pk_add_f32 v[164:165], v[164:165], v[198:199] op_sel_hi:[1,0]
	v_pk_add_f32 v[166:167], v[166:167], v[198:199] op_sel_hi:[1,0]
	v_pk_add_f32 v[168:169], v[168:169], v[198:199] op_sel_hi:[1,0]
	v_rcp_f32_e32 v162, v162
	v_rcp_f32_e32 v163, v163
	v_rcp_f32_e32 v164, v164
	v_rcp_f32_e32 v165, v165
	v_rcp_f32_e32 v166, v166
	v_rcp_f32_e32 v167, v167
	v_rcp_f32_e32 v168, v168
	v_rcp_f32_e32 v169, v169
	v_pk_mul_f32 v[162:163], v[160:161], v[162:163] op_sel_hi:[0,1]
	v_pk_mul_f32 v[164:165], v[160:161], v[164:165] op_sel_hi:[0,1]
	v_pk_mul_f32 v[166:167], v[160:161], v[166:167] op_sel_hi:[0,1]
	v_pk_mul_f32 v[168:169], v[160:161], v[168:169] op_sel_hi:[0,1]
	v_pk_mul_f32 v[8:9], v[8:9], v[162:163]
	v_pk_mul_f32 v[10:11], v[10:11], v[164:165]
	v_pk_mul_f32 v[0:1], v[0:1], v[166:167]
	v_pk_mul_f32 v[2:3], v[2:3], v[168:169]
	v_cvt_pk_bf16_f32 v250, v8, v9
	v_cvt_pk_bf16_f32 v251, v10, v11
	v_cvt_pk_bf16_f32 v252, v0, v1
	v_cvt_pk_bf16_f32 v253, v2, v3
	v_mov_b32_e32 v254, v155
	s_andn2_b64 vcc, exec, s[2:3]
	s_mov_b64 s[2:3], -1
	s_mov_b32 s101, 1
	s_mov_b32 s70, 1
	s_cbranch_vccz .Lswg_def_1613
	s_mov_b32 s70, 0
	v_add_u32_e32 v255, 0x2c000, v254
	global_store_dwordx4 v255, v[228:231], s[64:65]
	v_add_u32_e32 v244, 0x42000, v254
	global_store_dwordx4 v244, v[232:235], s[64:65]
	v_add_u32_e32 v255, 0xb0000, v254
	global_store_dwordx4 v255, v[236:239], s[64:65]
	v_add_u32_e32 v244, 0xc6000, v254
	global_store_dwordx4 v244, v[240:243], s[64:65]
	v_add_u32_e32 v255, 0xdc000, v254
	global_store_dwordx4 v255, v[246:249], s[64:65]
	v_add_u32_e32 v244, 0xf2000, v254
	global_store_dwordx4 v244, v[250:253], s[64:65]
	s_branch .LBB0_1609
